# grid barrier protocol at the 6 in-loop seams rewritten: XCD-last adds to all per-XCD generation words directly (removes the cross-XCD leader poll+rebroadcast hop); setup seam unchanged
# speedup vs baseline: 1.0225x; 1.0116x over previous
; #define LAS __attribute__((address_space(3)))
; __global__ void __launch_bounds__(512, 2) mk_fwd(Args a) {
;     extern __shared__ __attribute__((aligned(16))) unsigned char lds_raw[];
;     LAS unsigned char* lds = (LAS unsigned char*)lds_raw;
;     cg::grid_group grid = cg::this_grid();
;     const int G = gridDim.x;
;     if (threadIdx.x < 2) ((volatile LAS unsigned*)(lds + LDS_BARST))[threadIdx.x] = 0u;
;     __syncthreads();
;     if (a.ws == nullptr) grid.sync();
;     const XcdBarrier xbar = xcd_barrier_post((unsigned*)(a.ws + WS_BAR), (volatile LAS unsigned*)(lds + LDS_BARST));
_Z6mk_fwd4Args:
	s_load_dwordx8 s[4:11], s[0:1], 0x80
	s_load_dwordx4 s[88:91], s[0:1], 0xa0
	s_load_dword s18, s[0:1], 0xb0
	s_mov_b32 s3, 0
	v_writelane_b32 v255, s3, 54
	v_writelane_b32 v253, s2, 0
	v_and_b32_e32 v236, 0x3ff, v0
	v_cmp_gt_u32_e32 vcc, 2, v236
	s_waitcnt lgkmcnt(0)
	v_writelane_b32 v253, s4, 1
	s_nop 1
	v_writelane_b32 v253, s5, 2
	v_writelane_b32 v253, s6, 3
	v_writelane_b32 v253, s7, 4
	v_writelane_b32 v253, s8, 5
	v_writelane_b32 v253, s9, 6
	v_writelane_b32 v253, s10, 7
	v_writelane_b32 v253, s11, 8
	s_add_u32 s4, s0, 0xa8
	s_addc_u32 s5, s1, 0
	s_and_saveexec_b64 s[2:3], vcc
	v_lshl_add_u32 v1, v236, 2, 0
	v_add_u32_e32 v1, 0x23fc0, v1
	v_mov_b32_e32 v2, 0
	ds_write_b32 v1, v2
	s_or_b64 exec, exec, s[2:3]
	s_cmp_lg_u64 s[88:89], 0
	s_waitcnt lgkmcnt(0)
	s_barrier
	s_cbranch_scc1 .LBB0_14
	v_lshrrev_b32_e32 v1, 20, v0
	v_lshrrev_b32_e32 v0, 10, v0
	v_or_b32_e32 v0, v0, v1
	s_movk_i32 s2, 0x3ff
	v_and_or_b32 v0, v0, s2, v236
	v_cmp_eq_u32_e32 vcc, 0, v0
	s_barrier
	s_and_saveexec_b64 s[2:3], vcc
	s_cbranch_execz .LBB0_13
	buffer_wbl2 sc1
	s_load_dwordx2 s[4:5], s[4:5], 0x58
	s_mov_b64 s[6:7], exec
	v_mbcnt_lo_u32_b32 v0, s6, 0
	v_mbcnt_hi_u32_b32 v0, s7, v0
	v_cmp_eq_u32_e32 vcc, 0, v0
	s_waitcnt lgkmcnt(0)
	s_load_dword s10, s[4:5], 0x28
	s_and_saveexec_b64 s[8:9], vcc
	s_cbranch_execz .LBB0_6
	s_bcnt1_i32_b64 s6, s[6:7]
	v_mov_b32_e32 v1, 0
	v_mov_b32_e32 v2, s6
	global_atomic_add v1, v1, v2, s[4:5] offset:32 sc0

; __device__ __forceinline__ void xcd_barrier(const XcdBarrier& b) {
;     asm volatile("s_waitcnt vmcnt(0)" ::: "memory");
;     __syncthreads();
;     if (threadIdx.x == 0) {
;         unsigned* bar = b.bar;
;         __builtin_amdgcn_s_waitcnt(0);
;         unsigned nloc = b.st[0], nx = b.st[1];
;         if (nloc == 0u) { xcd_barrier_complete(bar, b.x, nloc, nx); b.st[0] = nloc; b.st[1] = nx; }
;         const unsigned old = xb_add(&bar[XB_XSUB(b.x)], 1u);
;         const unsigned gen = old / nloc;
;         if (old + 1u == (gen + 1u) * nloc) {
;             __builtin_amdgcn_fence(__ATOMIC_RELEASE, "agent");
;             asm volatile("s_waitcnt vmcnt(0)" ::: "memory");
;             const unsigned og = xb_add(&bar[XB_TOP], 1u);
;             const unsigned tg = og / nx;
;             __builtin_amdgcn_fence(__ATOMIC_ACQUIRE, "agent");
;             if (og + 1u == (tg + 1u) * nx) xb_add(&bar[XB_TOPGEN], 1u);
;             else XB_SPIN(xb_ld(&bar[XB_TOPGEN]) == tg, bar);
;             xb_add(&bar[XB_XGEN(b.x)], 1u);
;             asm volatile("s_waitcnt vmcnt(0)" ::: "memory");
;         } else {
;             __builtin_amdgcn_fence(__ATOMIC_ACQUIRE, "agent");
;             XB_SPIN(xb_ld(&bar[XB_XGEN(b.x)]) == gen, bar);
;             asm volatile("s_waitcnt vmcnt(0)" ::: "memory");
;         }
;     }
;     __syncthreads();
; }
; __device__ __forceinline__ void attn_unit(LAS unsigned char* lds, const Args& a, int layer, int b, int nb, int kh, float shift2) {
;     int tid_ = threadIdx.x; asm volatile("" : "+v"(tid_)); const int tid = tid_, lane = tid & 63, wid = tid >> 6;
;     LAS bf16_t* KS = (LAS bf16_t*)lds;
;     LAS bf16_t* VT = (LAS bf16_t*)(lds + 384 * KS_LD * 2);
;     const bf16_t* Qb = (const bf16_t*)(a.ws + WS_Q); const bf16_t* Kb = (const bf16_t*)(a.ws + WS_K); const bf16_t* Vb = (const bf16_t*)(a.ws + WS_V);
;     bf16_t* MIX = (bf16_t*)(a.ws + WS_MIX);
;     const float* qg = a.q_gain + layer * 64; const float* kg = a.k_gain + layer * 64;
;     const int hq = kh * 4 + (wid >> 1), n = lane & 31, hi = lane >> 5;
;     const int ib = (wid & 1) * 64;
;     const size_t tok0 = (size_t)b * SEQ + nb * 128 + ib + n;
;     const int part = tid & 7;
;     u32x4 kraw[6], vraw[6], qraw[2][4];
; #pragma unroll
;     for (int r = 0; r < 6; ++r) {
;         const int key = (tid >> 3) + 64 * r, pos = (nb - 1) * 128 + key;
.LBB0_388:
	s_waitcnt vmcnt(0)
	s_waitcnt vmcnt(0) lgkmcnt(0)
	s_barrier
	s_mov_b64 s[10:11], exec
	v_readlane_b32 s8, v253, 41
	v_readlane_b32 s9, v253, 42
	s_and_b64 s[8:9], s[10:11], s[8:9]
	s_mov_b64 exec, s[8:9]
	s_cbranch_execz .LBB0_440
	s_waitcnt vmcnt(0) lgkmcnt(0)
	v_readlane_b32 s22, v255, 54
	v_readlane_b32 s24, v254, 51
	v_readlane_b32 s8, v254, 25
	v_readlane_b32 s9, v254, 26
	v_readlane_b32 s20, v254, 27
	v_readlane_b32 s21, v254, 28
	s_add_u32 s22, s22, 1
	v_mov_b32_e32 v0, s24
	ds_read_b32 v2, v0
	s_add_u32 s8, s8, 0x2c00
	s_addc_u32 s9, s9, 0
	s_add_u32 s20, s20, 0x2c00
	s_addc_u32 s21, s21, 0
	v_writelane_b32 v255, s22, 54
	v_mov_b32_e32 v1, 1
	v_mov_b32_e32 v3, 0
	s_nop 1
	global_atomic_add v4, v3, v1, s[8:9] sc0
	s_waitcnt vmcnt(0) lgkmcnt(0)
	v_readfirstlane_b32 s24, v4
	v_readfirstlane_b32 s23, v2
	s_add_u32 s24, s24, 1
	s_mul_i32 s25, s23, s22
	s_cmp_lg_u32 s24, s25
	s_cbranch_scc1 .Lgd_notlast_0
	buffer_wbl2 sc1
	s_waitcnt vmcnt(0)
	v_readlane_b32 s8, v254, 29
	v_readlane_b32 s9, v254, 30
	v_mov_b32_e32 v5, s23
	s_add_u32 s8, s8, 0x1c00
	s_addc_u32 s9, s9, 0
	s_nop 4
	global_atomic_add v3, v5, s[8:9]
	global_atomic_add v3, v5, s[8:9] offset:256
	global_atomic_add v3, v5, s[8:9] offset:512
	global_atomic_add v3, v5, s[8:9] offset:768
	global_atomic_add v3, v5, s[8:9] offset:1024
	global_atomic_add v3, v5, s[8:9] offset:1280
	global_atomic_add v3, v5, s[8:9] offset:1536
	global_atomic_add v3, v5, s[8:9] offset:1792
	global_atomic_add v3, v5, s[8:9] offset:2048
	global_atomic_add v3, v5, s[8:9] offset:2304
	global_atomic_add v3, v5, s[8:9] offset:2560
	global_atomic_add v3, v5, s[8:9] offset:2816
	global_atomic_add v3, v5, s[8:9] offset:3072
	global_atomic_add v3, v5, s[8:9] offset:3328
	global_atomic_add v3, v5, s[8:9] offset:3584
	global_atomic_add v3, v5, s[8:9] offset:3840
.Lgd_notlast_0:
	buffer_inv sc1
	s_lshl_b32 s22, s22, 8
	s_mov_b32 s25, 0
.Lgd_poll_0:
	global_load_dword v6, v3, s[20:21] sc1
	s_waitcnt vmcnt(0)
	v_readfirstlane_b32 s24, v6
	s_cmp_ge_u32 s24, s22
	s_cbranch_scc1 .Lgd_done_0
	s_sleep 1
	s_add_u32 s25, s25, 1
	s_cmp_lt_u32 s25, 0x8000
	s_cbranch_scc1 .Lgd_poll_0
.Lgd_done_0:
	s_waitcnt vmcnt(0)
.LBB0_440:
	s_or_b64 exec, exec, s[10:11]
	v_readlane_b32 s8, v254, 63
	v_readlane_b32 s9, v255, 0
	v_readlane_b32 s10, v255, 1
	v_readlane_b32 s11, v255, 2
	s_add_u32 s8, s92, 0x9800000
	v_writelane_b32 v254, s8, 63
	s_addc_u32 s3, s93, 0
	s_add_u32 s53, s92, 0x8000
	v_writelane_b32 v255, s9, 0
	v_writelane_b32 v255, s10, 1
	v_writelane_b32 v255, s11, 2
	s_addc_u32 s1, s93, 0
	v_writelane_b32 v255, s1, 47
	s_cmp_gt_i32 s49, 63
	s_mov_b64 s[10:11], -1
	s_waitcnt lgkmcnt(0)
	s_barrier
	s_cbranch_scc0 .LBB0_512
	s_cmpk_gt_u32 s49, 0xbf
	s_cbranch_scc0 .LBB0_482
	v_and_b32_e32 v0, 63, v236
	v_readlane_b32 s10, v255, 45
	v_readlane_b32 s64, v253, 9
	v_readlane_b32 s70, v253, 15
	v_add_u32_e32 v0, s10, v0
	v_ashrrev_i32_e32 v1, 31, v0
	v_lshlrev_b64 v[0:1], 2, v[0:1]
	v_readlane_b32 s71, v253, 16
	v_readlane_b32 s72, v253, 17
	v_readlane_b32 s73, v253, 18
	v_lshl_add_u64 v[2:3], s[70:71], 0, v[0:1]
	global_load_dword v2, v[2:3], off
	v_lshl_add_u64 v[0:1], s[72:73], 0, v[0:1]
	global_load_dword v0, v[0:1], off
	v_and_b32_e32 v4, 64, v243
	v_add_u32_e32 v4, 64, v4
	v_xor_b32_e32 v5, 1, v243
	v_cmp_lt_i32_e32 vcc, v5, v4
	s_add_i32 s5, s49, 0xffffff40
	s_lshl_b32 s7, s49, 3
	v_cndmask_b32_e32 v5, v243, v5, vcc
	v_lshlrev_b32_e32 v92, 2, v5
	s_and_b32 s7, s7, 56
	s_lshr_b32 s8, s5, 3
	v_readlane_b32 s11, v255, 46
	s_add_i32 s7, s8, s7
	s_addk_i32 s7, 0x80
	s_mov_b32 s11, s59
	s_lshr_b32 s20, s7, 7
	s_bfe_u32 s8, s7, 0x60001
	s_bfe_u32 s5, s5, 0x10003
	s_mov_b32 s12, s10
	s_lshl_b64 s[10:11], s[10:11], 2
	v_mov_b32_e32 v89, v236
	s_add_u32 s16, s72, s10
	s_addc_u32 s17, s73, s11
	v_and_b32_e32 v90, 64, v89
	s_mov_b32 s21, s59
	s_lshl_b32 s7, s8, 7
	v_ashrrev_i32_e32 v98, 3, v89
	s_lshl_b64 s[20:21], s[20:21], 13
	v_or_b32_e32 v5, s7, v90
	v_add_u32_e32 v10, s7, v98
	s_lshl_b32 s7, s5, 7
	v_readlane_b32 s1, v254, 39
	v_and_b32_e32 v68, 7, v89
	s_add_u32 s22, s1, s7
	v_readlane_b32 s1, v254, 40
	s_addc_u32 s23, s1, 0
	v_lshlrev_b32_e32 v200, 4, v68
	v_readlane_b32 s1, v254, 41
	v_add_u32_e32 v6, 0xffffff80, v10
	v_readlane_b32 s14, v254, 43
	v_and_b32_e32 v91, 31, v89
	v_bfe_u32 v96, v89, 5, 1
	v_readlane_b32 s15, v254, 44
	v_or3_b32 v146, v5, v91, s20
	v_mov_b32_e32 v147, s21
	v_lshlrev_b32_e32 v80, 4, v96
	v_mov_b32_e32 v81, v201
	v_lshlrev_b32_e32 v40, 5, v68
	v_add_u32_e32 v88, 0, v200
	v_readlane_b32 s74, v253, 19
	v_readlane_b32 s75, v253, 20
	v_lshlrev_b32_e32 v95, 3, v96
	v_lshlrev_b32_e32 v188, 2, v96
	s_mov_b32 s13, 0
	v_writelane_b32 v255, s12, 45
	v_lshrrev_b32_e32 v190, 5, v90
	v_or_b32_e32 v191, 1, v190
	v_writelane_b32 v255, s13, 46
	v_or_b32_e32 v192, 8, v190
	v_readlane_b32 s65, v253, 10
	v_readlane_b32 s66, v253, 11
	v_readlane_b32 s67, v253, 12
	v_readlane_b32 s68, v253, 13
	v_readlane_b32 s69, v253, 14
	v_readlane_b32 s76, v253, 21
	v_readlane_b32 s77, v253, 22
	v_readlane_b32 s78, v253, 23
	v_readlane_b32 s79, v253, 24
	s_waitcnt vmcnt(1)
	v_and_b32_e32 v3, 0x7fffffff, v2
	ds_bpermute_b32 v3, v92, v3
	s_waitcnt vmcnt(0)
	v_and_b32_e32 v1, 0x7fffffff, v0
	ds_bpermute_b32 v1, v92, v1
	v_max_f32_e64 v0, |v0|, |v0|
	v_max_f32_e64 v2, |v2|, |v2|
	s_waitcnt lgkmcnt(1)
	v_max_f32_e32 v3, v3, v3
	v_max_f32_e32 v2, v2, v3
	s_waitcnt lgkmcnt(0)
	v_max_f32_e32 v1, v1, v1
	v_max_f32_e32 v0, v0, v1
	v_xor_b32_e32 v1, 2, v243
	v_cmp_lt_i32_e32 vcc, v1, v4
	s_nop 1
	v_cndmask_b32_e32 v1, v243, v1, vcc
	v_lshlrev_b32_e32 v93, 2, v1
	ds_bpermute_b32 v1, v93, v2
	s_waitcnt lgkmcnt(0)
; __device__ __forceinline__ void attn_unit(LAS unsigned char* lds, const Args& a, int layer, int b, int nb, int kh, float shift2) {
;     ...
;     const int hq = kh * 4 + (wid >> 1), n = lane & 31, hi = lane >> 5;
;     const int ib = (wid & 1) * 64;
;     const size_t tok0 = (size_t)b * SEQ + nb * 128 + ib + n;
;     const int part = tid & 7;
;     u32x4 kraw[6], vraw[6], qraw[2][4];
; #pragma unroll
;     for (int r = 0; r < 6; ++r) {
;         const int key = (tid >> 3) + 64 * r, pos = (nb - 1) * 128 + key;
;         const size_t row = (size_t)b * SEQ + ((pos >= 0 && pos < SEQ) ? pos : 0);
;         kraw[r] = *(const u32x4*)(Kb + row * 128 + kh * 64 + part * 8);
;         vraw[r] = *(const u32x4*)(Vb + row * 128 + kh * 64 + part * 8);
;     }
; #pragma unroll
;     for (int qt = 0; qt < 2; ++qt)
; #pragma unroll
;         for (int ks = 0; ks < 4; ++ks) qraw[qt][ks] = *(const u32x4*)(Qb + (tok0 + 32 * qt) * 512 + hq * 64 + ks * 16 + hi * 8);
;     const f32x4 kg0 = *(const f32x4*)(kg + part * 8), kg1 = *(const f32x4*)(kg + part * 8 + 4);
	v_max_f32_e32 v1, v1, v1
	v_max_f32_e32 v1, v2, v1
	ds_bpermute_b32 v2, v93, v0
	s_waitcnt lgkmcnt(0)
	v_max_f32_e32 v2, v2, v2
	v_max_f32_e32 v0, v0, v2
	v_xor_b32_e32 v2, 4, v243
	v_cmp_lt_i32_e32 vcc, v2, v4
	s_nop 1
	v_cndmask_b32_e32 v2, v243, v2, vcc
	v_lshlrev_b32_e32 v94, 2, v2
	ds_bpermute_b32 v2, v94, v1
	s_waitcnt lgkmcnt(0)
	v_max_f32_e32 v2, v2, v2
	v_max_f32_e32 v1, v1, v2
	ds_bpermute_b32 v2, v94, v0
	s_waitcnt lgkmcnt(0)
	v_max_f32_e32 v2, v2, v2
	v_max_f32_e32 v0, v0, v2
	v_xor_b32_e32 v2, 8, v243
	v_cmp_lt_i32_e32 vcc, v2, v4
	s_nop 1
	v_cndmask_b32_e32 v2, v243, v2, vcc
	v_lshlrev_b32_e32 v2, 2, v2
	ds_bpermute_b32 v3, v2, v1
	ds_bpermute_b32 v2, v2, v0
	s_waitcnt lgkmcnt(1)
	v_max_f32_e32 v3, v3, v3
	s_waitcnt lgkmcnt(0)
	v_max_f32_e32 v2, v2, v2
	v_max_f32_e32 v0, v0, v2
	v_xor_b32_e32 v2, 16, v243
	v_cmp_lt_i32_e32 vcc, v2, v4
	v_max_f32_e32 v1, v1, v3
	s_nop 0
	v_cndmask_b32_e32 v2, v243, v2, vcc
	v_lshlrev_b32_e32 v2, 2, v2
	ds_bpermute_b32 v3, v2, v1
	ds_bpermute_b32 v2, v2, v0
	s_waitcnt lgkmcnt(1)
	v_max_f32_e32 v3, v3, v3
	s_waitcnt lgkmcnt(0)
	v_max_f32_e32 v2, v2, v2
	v_max_f32_e32 v0, v0, v2
	v_xor_b32_e32 v2, 32, v243
	v_cmp_lt_i32_e32 vcc, v2, v4
	v_max_f32_e32 v1, v1, v3
	v_ashrrev_i32_e32 v4, 7, v89
	v_cndmask_b32_e32 v2, v243, v2, vcc
	v_lshlrev_b32_e32 v185, 2, v2
	ds_bpermute_b32 v2, v185, v1
	v_lshl_add_u32 v97, s5, 2, v4
	v_lshlrev_b32_e32 v144, 6, v97
	v_ashrrev_i32_e32 v145, 31, v144
	s_waitcnt lgkmcnt(0)
	v_max_f32_e32 v2, v2, v2
	v_max_f32_e32 v1, v1, v2
	ds_bpermute_b32 v2, v185, v0
	v_mul_f32_e32 v1, 0x41000000, v1
	s_waitcnt lgkmcnt(0)
	v_max_f32_e32 v2, v2, v2
	v_max_f32_e32 v0, v0, v2
	v_mul_f32_e32 v0, v0, v1
	v_mul_f32_e32 v186, 0x3fb8aa3b, v0
	v_lshl_add_u64 v[0:1], s[22:23], 0, v[200:201]
	s_add_u32 s22, s1, s7
	v_readlane_b32 s1, v254, 42
	s_addc_u32 s23, s1, 0
	s_movk_i32 s1, 0x2000
	v_cmp_gt_u32_e32 vcc, s1, v6
	v_lshl_add_u64 v[2:3], s[22:23], 0, v[200:201]
	s_add_u32 s10, s70, s10
	v_cndmask_b32_e32 v6, 0, v6, vcc
	v_ashrrev_i32_e32 v7, 31, v6
	v_lshl_add_u64 v[6:7], s[20:21], 0, v[6:7]
	v_lshlrev_b64 v[6:7], 8, v[6:7]
	v_lshl_add_u64 v[8:9], v[0:1], 0, v[6:7]
	global_load_dwordx4 v[60:63], v[8:9], off
	v_lshl_add_u64 v[66:67], v[2:3], 0, v[6:7]
	v_subrev_u32_e32 v6, 64, v10
	v_cmp_gt_u32_e32 vcc, s1, v6
	s_addc_u32 s11, s71, s11
	v_mov_b32_e32 v200, v201
	v_cndmask_b32_e32 v6, 0, v6, vcc
	v_ashrrev_i32_e32 v7, 31, v6
	v_lshl_add_u64 v[6:7], s[20:21], 0, v[6:7]
	v_lshlrev_b64 v[6:7], 8, v[6:7]
	v_cmp_gt_u32_e32 vcc, s1, v10
	v_lshl_add_u64 v[8:9], v[0:1], 0, v[6:7]
	v_lshl_add_u64 v[64:65], v[2:3], 0, v[6:7]
	v_cndmask_b32_e32 v6, 0, v10, vcc
	v_ashrrev_i32_e32 v7, 31, v6
	v_lshl_add_u64 v[6:7], s[20:21], 0, v[6:7]
	v_lshlrev_b64 v[6:7], 8, v[6:7]
	global_load_dwordx4 v[52:55], v[8:9], off
	v_lshl_add_u64 v[8:9], v[0:1], 0, v[6:7]
	v_lshl_add_u64 v[72:73], v[2:3], 0, v[6:7]
	v_add_u32_e32 v6, 64, v10
	v_cmp_gt_u32_e32 vcc, s1, v6
	global_load_dwordx4 v[56:59], v[8:9], off
	s_add_i32 s8, s8, -1
	v_cndmask_b32_e32 v6, 0, v6, vcc
	v_ashrrev_i32_e32 v7, 31, v6
	v_lshl_add_u64 v[6:7], s[20:21], 0, v[6:7]
	v_lshlrev_b64 v[6:7], 8, v[6:7]
	v_lshl_add_u64 v[8:9], v[0:1], 0, v[6:7]
	v_lshl_add_u64 v[74:75], v[2:3], 0, v[6:7]
	v_add_u32_e32 v6, 0x80, v10
	v_cmp_gt_u32_e32 vcc, s1, v6
	global_load_dwordx4 v[48:51], v[8:9], off
	v_mov_b64_e32 v[148:149], v[200:201]
	v_cndmask_b32_e32 v6, 0, v6, vcc
	v_ashrrev_i32_e32 v7, 31, v6
	v_lshl_add_u64 v[6:7], s[20:21], 0, v[6:7]
	v_lshlrev_b64 v[6:7], 8, v[6:7]
	v_lshl_add_u64 v[8:9], v[0:1], 0, v[6:7]
	v_lshl_add_u64 v[84:85], v[2:3], 0, v[6:7]
	v_add_u32_e32 v6, 0xc0, v10
	v_cmp_gt_u32_e32 vcc, s1, v6
	global_load_dwordx4 v[44:47], v[8:9], off
	s_movk_i32 s1, 0x90
	v_cndmask_b32_e32 v6, 0, v6, vcc
	v_ashrrev_i32_e32 v7, 31, v6
	v_lshl_add_u64 v[6:7], s[20:21], 0, v[6:7]
	v_lshlrev_b64 v[6:7], 8, v[6:7]
	v_lshl_add_u64 v[0:1], v[0:1], 0, v[6:7]
	global_load_dwordx4 v[32:35], v[0:1], off
	v_lshl_add_u64 v[0:1], v[144:145], 1, s[14:15]
	v_lshl_add_u64 v[86:87], v[2:3], 0, v[6:7]
	v_lshl_add_u64 v[0:1], v[0:1], 0, v[80:81]
	v_lshlrev_b64 v[2:3], 10, v[146:147]
	v_lshl_add_u64 v[4:5], v[0:1], 0, v[2:3]
	v_or_b32_e32 v2, 0x8000, v2
	v_lshl_add_u64 v[12:13], v[0:1], 0, v[2:3]
	global_load_dwordx4 v[16:19], v[4:5], off
	global_load_dwordx4 v[20:23], v[4:5], off offset:32
	global_load_dwordx4 v[24:27], v[4:5], off offset:64
	global_load_dwordx4 v[28:31], v[4:5], off offset:96
	global_load_dwordx4 v[0:3], v[12:13], off
	s_nop 0
	global_load_dwordx4 v[4:7], v[12:13], off offset:32
	global_load_dwordx4 v[8:11], v[12:13], off offset:64
	s_nop 0
	global_load_dwordx4 v[12:15], v[12:13], off offset:96
	s_nop 0
	global_load_dwordx4 v[36:39], v40, s[16:17] offset:16
	s_nop 0
	global_load_dwordx4 v[40:43], v40, s[16:17]
	v_mul_u32_u24_e32 v81, 0x1830, v68
	v_readlane_b32 s14, v254, 53
	v_readlane_b32 s15, v254, 54
	s_waitcnt vmcnt(15)
	v_lshlrev_b32_e32 v100, 16, v60
	v_and_b32_e32 v101, 0xffff0000, v60
	v_lshlrev_b32_e32 v78, 16, v61
	v_and_b32_e32 v79, 0xffff0000, v61
	v_pk_mul_f32 v[60:61], v[100:101], v[100:101]
	v_pk_mul_f32 v[82:83], v[78:79], v[78:79]
	v_add_f32_e32 v60, v60, v61
	v_lshlrev_b32_e32 v70, 16, v62
	v_and_b32_e32 v71, 0xffff0000, v62
	v_add_f32_e32 v60, v82, v60
	v_lshlrev_b32_e32 v76, 16, v63
	v_and_b32_e32 v77, 0xffff0000, v63
	v_pk_mul_f32 v[62:63], v[70:71], v[70:71]
	v_add_f32_e32 v60, v83, v60
	v_add_f32_e32 v60, v62, v60
	v_pk_mul_f32 v[68:69], v[76:77], v[76:77]
	v_add_f32_e32 v60, v63, v60
	v_add_f32_e32 v60, v68, v60
	v_add_f32_e32 v60, v69, v60
	ds_bpermute_b32 v61, v92, v60
	v_mad_u64_u32 v[82:83], s[16:17], v98, s1, v[88:89]
	s_waitcnt vmcnt(14)
; #define LAS __attribute__((address_space(3)))
; __device__ __forceinline__ unsigned pk2(float lo, float hi) { f32x2 v = {lo, hi}; bf2_t b = __builtin_convertvector(v, bf2_t); return __builtin_bit_cast(unsigned, b); }
; __device__ __forceinline__ void attn_unit(LAS unsigned char* lds, const Args& a, int layer, int b, int nb, int kh, float shift2) {
;     ...
;     for (int r = 0; r < 6; ++r) {
;         const int key = (tid >> 3) + 64 * r;
;         const u32x4 kr = kraw[r], vr = vraw[r];
;         float kf[8] = {bflo(kr.x), bfhi(kr.x), bflo(kr.y), bfhi(kr.y), bflo(kr.z), bfhi(kr.z), bflo(kr.w), bfhi(kr.w)};
;         float ss = 0.f;
; #pragma unroll
;         for (int e = 0; e < 8; ++e) ss += kf[e] * kf[e];
;         ss += __shfl_xor(ss, 1); ss += __shfl_xor(ss, 2); ss += __shfl_xor(ss, 4);
;         const float sc = __builtin_amdgcn_rsqf(ss * (1.0f / 64.0f) + EPS);
;         u32x4 o; o.x = pk2(kf[0] * sc * kg0[0], kf[1] * sc * kg0[1]); o.y = pk2(kf[2] * sc * kg0[2], kf[3] * sc * kg0[3]);
;         o.z = pk2(kf[4] * sc * kg1[0], kf[5] * sc * kg1[1]); o.w = pk2(kf[6] * sc * kg1[2], kf[7] * sc * kg1[3]);
;         *(LAS u32x4*)(KS + key * KS_LD + part * 8) = o;
;         LAS bf16_t* vp = VT + (part * 8) * VT_LD + key;
;         vp[0 * VT_LD] = (bf16_t)(vr.x & 0xffffu); vp[1 * VT_LD] = (bf16_t)(vr.x >> 16);
;         vp[2 * VT_LD] = (bf16_t)(vr.y & 0xffffu); vp[3 * VT_LD] = (bf16_t)(vr.y >> 16);
;         vp[4 * VT_LD] = (bf16_t)(vr.z & 0xffffu); vp[5 * VT_LD] = (bf16_t)(vr.z >> 16);
;         vp[6 * VT_LD] = (bf16_t)(vr.w & 0xffffu); vp[7 * VT_LD] = (bf16_t)(vr.w >> 16);
;     }
	v_and_b32_e32 v99, 0xffff0000, v53
	s_movk_i32 s1, 0xff80
	s_waitcnt lgkmcnt(0)
	v_add_f32_e32 v60, v60, v61
	ds_bpermute_b32 v61, v93, v60
	s_waitcnt lgkmcnt(0)
	v_add_f32_e32 v60, v60, v61
	ds_bpermute_b32 v61, v94, v60
	s_waitcnt lgkmcnt(0)
	v_add_f32_e32 v60, v60, v61
	v_fmamk_f32 v60, v60, 0x3c800000, v239
	v_rsq_f32_e32 v60, v60
	s_waitcnt vmcnt(9)
	v_lshlrev_b32_e32 v114, 16, v17
	v_pk_mul_f32 v[62:63], v[60:61], v[100:101] op_sel_hi:[0,1]
	v_and_b32_e32 v115, 0xffff0000, v17
	v_lshlrev_b32_e32 v116, 16, v16
	v_and_b32_e32 v117, 0xffff0000, v16
	s_waitcnt vmcnt(0)
	v_pk_mul_f32 v[62:63], v[40:41], v[62:63]
	v_lshlrev_b32_e32 v110, 16, v18
	v_cvt_pk_bf16_f32 v68, v62, v63
	v_pk_mul_f32 v[62:63], v[60:61], v[78:79] op_sel_hi:[0,1]
	v_pk_mul_f32 v[62:63], v[42:43], v[62:63]
	v_and_b32_e32 v111, 0xffff0000, v18
	v_cvt_pk_bf16_f32 v69, v62, v63
	v_pk_mul_f32 v[62:63], v[60:61], v[70:71] op_sel_hi:[0,1]
	v_pk_mul_f32 v[60:61], v[60:61], v[76:77] op_sel_hi:[0,1]
	v_pk_mul_f32 v[62:63], v[36:37], v[62:63]
	v_pk_mul_f32 v[60:61], v[38:39], v[60:61]
	v_cvt_pk_bf16_f32 v70, v62, v63
	v_cvt_pk_bf16_f32 v71, v60, v61
	global_load_dwordx4 v[100:103], v[66:67], off
	global_load_dwordx4 v[104:107], v[64:65], off
	global_load_dwordx4 v[76:79], v[72:73], off
	s_nop 0
	global_load_dwordx4 v[72:75], v[74:75], off
	s_nop 0
	global_load_dwordx4 v[64:67], v[84:85], off
	global_load_dwordx4 v[60:63], v[86:87], off
	ds_write_b128 v82, v[68:71]
	v_lshlrev_b32_e32 v68, 1, v98
	v_add3_u32 v68, v88, v81, v68
	v_lshlrev_b32_e32 v98, 16, v53
	v_lshlrev_b32_e32 v86, 16, v54
	v_and_b32_e32 v87, 0xffff0000, v54
	s_waitcnt vmcnt(5)
	ds_write_b16 v68, v100 offset:55296
	ds_write_b16_d16_hi v68, v100 offset:56072
	ds_write_b16 v68, v101 offset:56848
	ds_write_b16_d16_hi v68, v101 offset:57624
	ds_write_b16 v68, v102 offset:58400
	ds_write_b16_d16_hi v68, v102 offset:59176
	ds_write_b16 v68, v103 offset:59952
	ds_write_b16_d16_hi v68, v103 offset:60728
	v_lshlrev_b32_e32 v102, 16, v52
	v_and_b32_e32 v103, 0xffff0000, v52
	v_pk_mul_f32 v[52:53], v[102:103], v[102:103]
	v_pk_mul_f32 v[100:101], v[98:99], v[98:99]
	v_add_f32_e32 v52, v52, v53
	v_add_f32_e32 v52, v100, v52
	v_lshlrev_b32_e32 v70, 16, v55
	v_and_b32_e32 v71, 0xffff0000, v55
	v_pk_mul_f32 v[54:55], v[86:87], v[86:87]
	v_add_f32_e32 v52, v101, v52
	v_add_f32_e32 v52, v54, v52
	v_pk_mul_f32 v[84:85], v[70:71], v[70:71]
	v_add_f32_e32 v52, v55, v52
	v_add_f32_e32 v52, v84, v52
	v_add_f32_e32 v52, v85, v52
	ds_bpermute_b32 v53, v92, v52
	v_and_b32_e32 v69, 0xffff0000, v30
	v_pk_mul_f32 v[112:113], v[114:115], v[114:115]
	v_pk_mul_f32 v[16:17], v[116:117], v[116:117]
	v_add_f32_e32 v81, v112, v113
	s_waitcnt lgkmcnt(0)
	v_add_f32_e32 v52, v52, v53
	ds_bpermute_b32 v53, v93, v52
	v_add_f32_e32 v16, v16, v17
	v_add_f32_e32 v16, v16, v81
	v_lshlrev_b32_e32 v100, 16, v21
	v_and_b32_e32 v101, 0xffff0000, v21
	s_waitcnt lgkmcnt(0)
	v_add_f32_e32 v52, v52, v53
	ds_bpermute_b32 v53, v94, v52
	s_waitcnt lgkmcnt(0)
	v_add_f32_e32 v52, v52, v53
	v_fmamk_f32 v52, v52, 0x3c800000, v239
	v_rsq_f32_e32 v84, v52
	s_nop 0
	v_pk_mul_f32 v[52:53], v[84:85], v[102:103] op_sel_hi:[0,1]
	v_pk_mul_f32 v[54:55], v[84:85], v[98:99] op_sel_hi:[0,1]
	v_pk_mul_f32 v[52:53], v[40:41], v[52:53]
	v_pk_mul_f32 v[54:55], v[42:43], v[54:55]
	v_cvt_pk_bf16_f32 v52, v52, v53
	v_cvt_pk_bf16_f32 v53, v54, v55
	v_pk_mul_f32 v[54:55], v[84:85], v[86:87] op_sel_hi:[0,1]
	v_pk_mul_f32 v[70:71], v[84:85], v[70:71] op_sel_hi:[0,1]
	v_lshlrev_b32_e32 v98, 16, v56
	v_and_b32_e32 v99, 0xffff0000, v56
	v_pk_mul_f32 v[54:55], v[36:37], v[54:55]
	v_pk_mul_f32 v[70:71], v[38:39], v[70:71]
	v_lshlrev_b32_e32 v84, 16, v57
	v_and_b32_e32 v85, 0xffff0000, v57
	v_pk_mul_f32 v[56:57], v[98:99], v[98:99]
	v_cvt_pk_bf16_f32 v54, v54, v55
	v_cvt_pk_bf16_f32 v55, v70, v71
	v_pk_mul_f32 v[86:87], v[84:85], v[84:85]
	v_add_f32_e32 v56, v56, v57
	ds_write_b128 v82, v[52:55] offset:9216
	s_waitcnt vmcnt(4)
	ds_write_b16 v68, v104 offset:55424
	ds_write_b16_d16_hi v68, v104 offset:56200
	ds_write_b16 v68, v105 offset:56976
	ds_write_b16_d16_hi v68, v105 offset:57752
	ds_write_b16 v68, v106 offset:58528
	ds_write_b16_d16_hi v68, v106 offset:59304
	ds_write_b16 v68, v107 offset:60080
	ds_write_b16_d16_hi v68, v107 offset:60856
	v_lshlrev_b32_e32 v54, 16, v58
	v_and_b32_e32 v55, 0xffff0000, v58
	v_add_f32_e32 v56, v86, v56
	v_lshlrev_b32_e32 v70, 16, v59
	v_and_b32_e32 v71, 0xffff0000, v59
	v_pk_mul_f32 v[58:59], v[54:55], v[54:55]
	v_add_f32_e32 v56, v87, v56
	v_add_f32_e32 v56, v58, v56
	v_pk_mul_f32 v[52:53], v[70:71], v[70:71]
	v_add_f32_e32 v56, v59, v56
	v_add_f32_e32 v52, v52, v56
	v_add_f32_e32 v52, v53, v52
	ds_bpermute_b32 v53, v92, v52
	v_lshlrev_b32_e32 v106, 16, v19
	v_and_b32_e32 v107, 0xffff0000, v19
	v_pk_mul_f32 v[18:19], v[110:111], v[110:111]
	v_lshlrev_b32_e32 v104, 16, v20
	s_waitcnt lgkmcnt(0)
	v_add_f32_e32 v52, v52, v53
	ds_bpermute_b32 v53, v93, v52
	v_and_b32_e32 v105, 0xffff0000, v20
	v_pk_mul_f32 v[108:109], v[106:107], v[106:107]
	v_add_f32_e32 v17, v18, v19
	v_pk_mul_f32 v[20:21], v[104:105], v[104:105]
	s_waitcnt lgkmcnt(0)
	v_add_f32_e32 v52, v52, v53
	ds_bpermute_b32 v53, v94, v52
	v_add_f32_e32 v16, v17, v16
	v_pk_mul_f32 v[102:103], v[100:101], v[100:101]
	v_add_f32_e32 v17, v20, v21
	v_lshlrev_b32_e32 v86, 16, v23
	s_waitcnt lgkmcnt(0)
; #define LAS __attribute__((address_space(3)))
; __device__ __forceinline__ unsigned pk2(float lo, float hi) { f32x2 v = {lo, hi}; bf2_t b = __builtin_convertvector(v, bf2_t); return __builtin_bit_cast(unsigned, b); }
; __device__ __forceinline__ void attn_unit(LAS unsigned char* lds, const Args& a, int layer, int b, int nb, int kh, float shift2) {
;     ...
;     for (int r = 0; r < 6; ++r) {
;         const int key = (tid >> 3) + 64 * r;
;         const u32x4 kr = kraw[r], vr = vraw[r];
;         float kf[8] = {bflo(kr.x), bfhi(kr.x), bflo(kr.y), bfhi(kr.y), bflo(kr.z), bfhi(kr.z), bflo(kr.w), bfhi(kr.w)};
;         float ss = 0.f;
; #pragma unroll
;         for (int e = 0; e < 8; ++e) ss += kf[e] * kf[e];
;         ss += __shfl_xor(ss, 1); ss += __shfl_xor(ss, 2); ss += __shfl_xor(ss, 4);
;         const float sc = __builtin_amdgcn_rsqf(ss * (1.0f / 64.0f) + EPS);
;         u32x4 o; o.x = pk2(kf[0] * sc * kg0[0], kf[1] * sc * kg0[1]); o.y = pk2(kf[2] * sc * kg0[2], kf[3] * sc * kg0[3]);
;         o.z = pk2(kf[4] * sc * kg1[0], kf[5] * sc * kg1[1]); o.w = pk2(kf[6] * sc * kg1[2], kf[7] * sc * kg1[3]);
;         *(LAS u32x4*)(KS + key * KS_LD + part * 8) = o;
;         LAS bf16_t* vp = VT + (part * 8) * VT_LD + key;
;         vp[0 * VT_LD] = (bf16_t)(vr.x & 0xffffu); vp[1 * VT_LD] = (bf16_t)(vr.x >> 16);
;         vp[2 * VT_LD] = (bf16_t)(vr.y & 0xffffu); vp[3 * VT_LD] = (bf16_t)(vr.y >> 16);
;         vp[4 * VT_LD] = (bf16_t)(vr.z & 0xffffu); vp[5 * VT_LD] = (bf16_t)(vr.z >> 16);
;         vp[6 * VT_LD] = (bf16_t)(vr.w & 0xffffu); vp[7 * VT_LD] = (bf16_t)(vr.w >> 16);
;     }
	v_add_f32_e32 v52, v52, v53
	v_fmamk_f32 v52, v52, 0x3c800000, v239
	v_rsq_f32_e32 v56, v52
	v_and_b32_e32 v87, 0xffff0000, v23
	v_pk_mul_f32 v[52:53], v[56:57], v[98:99] op_sel_hi:[0,1]
	v_pk_mul_f32 v[58:59], v[56:57], v[84:85] op_sel_hi:[0,1]
	v_pk_mul_f32 v[54:55], v[56:57], v[54:55] op_sel_hi:[0,1]
	v_pk_mul_f32 v[56:57], v[56:57], v[70:71] op_sel_hi:[0,1]
	v_pk_mul_f32 v[52:53], v[40:41], v[52:53]
	v_pk_mul_f32 v[58:59], v[42:43], v[58:59]
	v_pk_mul_f32 v[54:55], v[36:37], v[54:55]
	v_pk_mul_f32 v[56:57], v[38:39], v[56:57]
	v_cvt_pk_bf16_f32 v52, v52, v53
	v_cvt_pk_bf16_f32 v53, v58, v59
	v_cvt_pk_bf16_f32 v54, v54, v55
	v_cvt_pk_bf16_f32 v55, v56, v57
	ds_write_b128 v82, v[52:55] offset:18432
	s_waitcnt vmcnt(3)
	ds_write_b16 v68, v76 offset:55552
	ds_write_b16_d16_hi v68, v76 offset:56328
	ds_write_b16 v68, v77 offset:57104
	ds_write_b16_d16_hi v68, v77 offset:57880
	ds_write_b16 v68, v78 offset:58656
	ds_write_b16_d16_hi v68, v78 offset:59432
	ds_write_b16 v68, v79 offset:60208
	ds_write_b16_d16_hi v68, v79 offset:60984
	v_lshlrev_b32_e32 v76, 16, v48
	v_and_b32_e32 v77, 0xffff0000, v48
	v_lshlrev_b32_e32 v58, 16, v49
	v_and_b32_e32 v59, 0xffff0000, v49
	v_pk_mul_f32 v[48:49], v[76:77], v[76:77]
	v_pk_mul_f32 v[70:71], v[58:59], v[58:59]
	v_add_f32_e32 v48, v48, v49
	v_lshlrev_b32_e32 v56, 16, v50
	v_and_b32_e32 v57, 0xffff0000, v50
	v_add_f32_e32 v48, v70, v48
	v_lshlrev_b32_e32 v52, 16, v51
	v_and_b32_e32 v53, 0xffff0000, v51
	v_pk_mul_f32 v[50:51], v[56:57], v[56:57]
	v_add_f32_e32 v48, v71, v48
	v_add_f32_e32 v48, v50, v48
	v_pk_mul_f32 v[54:55], v[52:53], v[52:53]
	v_add_f32_e32 v48, v51, v48
	v_add_f32_e32 v48, v54, v48
	v_add_f32_e32 v48, v55, v48
	ds_bpermute_b32 v49, v92, v48
	v_mov_b32_e32 v71, v69
	v_lshlrev_b32_e32 v98, 16, v22
	v_and_b32_e32 v99, 0xffff0000, v22
	v_pk_mul_f32 v[22:23], v[98:99], v[98:99]
	s_waitcnt lgkmcnt(0)
	v_add_f32_e32 v48, v48, v49
	ds_bpermute_b32 v49, v93, v48
	v_lshlrev_b32_e32 v84, 16, v24
	v_and_b32_e32 v85, 0xffff0000, v24
	s_waitcnt lgkmcnt(0)
	v_add_f32_e32 v48, v48, v49
	ds_bpermute_b32 v49, v94, v48
	s_waitcnt lgkmcnt(0)
	v_add_f32_e32 v48, v48, v49
	v_fmamk_f32 v48, v48, 0x3c800000, v239
	v_rsq_f32_e32 v54, v48
	s_nop 0
	v_pk_mul_f32 v[48:49], v[54:55], v[76:77] op_sel_hi:[0,1]
	v_pk_mul_f32 v[50:51], v[54:55], v[58:59] op_sel_hi:[0,1]
	v_pk_mul_f32 v[48:49], v[40:41], v[48:49]
	v_pk_mul_f32 v[50:51], v[42:43], v[50:51]
	v_lshlrev_b32_e32 v58, 16, v44
	v_and_b32_e32 v59, 0xffff0000, v44
	v_cvt_pk_bf16_f32 v48, v48, v49
	v_cvt_pk_bf16_f32 v49, v50, v51
	v_pk_mul_f32 v[50:51], v[54:55], v[56:57] op_sel_hi:[0,1]
	v_pk_mul_f32 v[52:53], v[54:55], v[52:53] op_sel_hi:[0,1]
	v_lshlrev_b32_e32 v54, 16, v45
	v_and_b32_e32 v55, 0xffff0000, v45
	v_pk_mul_f32 v[44:45], v[58:59], v[58:59]
	v_pk_mul_f32 v[50:51], v[36:37], v[50:51]
	v_pk_mul_f32 v[52:53], v[38:39], v[52:53]
	v_pk_mul_f32 v[56:57], v[54:55], v[54:55]
	v_add_f32_e32 v44, v44, v45
	v_cvt_pk_bf16_f32 v50, v50, v51
	v_cvt_pk_bf16_f32 v51, v52, v53
	v_lshlrev_b32_e32 v52, 16, v46
	v_and_b32_e32 v53, 0xffff0000, v46
	v_add_f32_e32 v44, v56, v44
	ds_write_b128 v82, v[48:51] offset:27648
	s_waitcnt vmcnt(2)
	ds_write_b16 v68, v72 offset:55680
	ds_write_b16_d16_hi v68, v72 offset:56456
	ds_write_b16 v68, v73 offset:57232
	ds_write_b16_d16_hi v68, v73 offset:58008
	ds_write_b16 v68, v74 offset:58784
	ds_write_b16_d16_hi v68, v74 offset:59560
	ds_write_b16 v68, v75 offset:60336
	ds_write_b16_d16_hi v68, v75 offset:61112
	v_lshlrev_b32_e32 v48, 16, v47
	v_and_b32_e32 v49, 0xffff0000, v47
	v_pk_mul_f32 v[46:47], v[52:53], v[52:53]
	v_add_f32_e32 v44, v57, v44
	v_add_f32_e32 v44, v46, v44
	v_pk_mul_f32 v[50:51], v[48:49], v[48:49]
	v_add_f32_e32 v44, v47, v44
	v_add_f32_e32 v44, v50, v44
	v_add_f32_e32 v44, v51, v44
	ds_bpermute_b32 v45, v92, v44
	v_and_b32_e32 v73, 0xffff0000, v28
	v_lshlrev_b32_e32 v72, 16, v28
	v_mov_b32_e32 v75, v73
	v_and_b32_e32 v77, 0xffff0000, v26
	s_waitcnt lgkmcnt(0)
	v_add_f32_e32 v44, v44, v45
	ds_bpermute_b32 v45, v93, v44
	v_lshlrev_b32_e32 v76, 16, v26
	v_mov_b32_e32 v79, v77
	s_waitcnt lgkmcnt(0)
	v_add_f32_e32 v44, v44, v45
	ds_bpermute_b32 v45, v94, v44
	s_waitcnt lgkmcnt(0)
	v_add_f32_e32 v44, v44, v45
	v_fmamk_f32 v44, v44, 0x3c800000, v239
	v_rsq_f32_e32 v50, v44
	s_nop 0
	v_pk_mul_f32 v[44:45], v[50:51], v[58:59] op_sel_hi:[0,1]
	v_pk_mul_f32 v[46:47], v[50:51], v[54:55] op_sel_hi:[0,1]
	v_pk_mul_f32 v[44:45], v[40:41], v[44:45]
	v_pk_mul_f32 v[46:47], v[42:43], v[46:47]
	v_lshlrev_b32_e32 v54, 16, v32
	v_and_b32_e32 v55, 0xffff0000, v32
	v_cvt_pk_bf16_f32 v44, v44, v45
	v_cvt_pk_bf16_f32 v45, v46, v47
	v_pk_mul_f32 v[46:47], v[50:51], v[52:53] op_sel_hi:[0,1]
	v_pk_mul_f32 v[48:49], v[50:51], v[48:49] op_sel_hi:[0,1]
	v_lshlrev_b32_e32 v50, 16, v33
	v_and_b32_e32 v51, 0xffff0000, v33
	v_pk_mul_f32 v[32:33], v[54:55], v[54:55]
	v_pk_mul_f32 v[46:47], v[36:37], v[46:47]
	v_pk_mul_f32 v[48:49], v[38:39], v[48:49]
	v_pk_mul_f32 v[52:53], v[50:51], v[50:51]
	v_add_f32_e32 v32, v32, v33
	v_cvt_pk_bf16_f32 v46, v46, v47
	v_cvt_pk_bf16_f32 v47, v48, v49
	v_lshlrev_b32_e32 v48, 16, v34
	v_and_b32_e32 v49, 0xffff0000, v34
	v_add_f32_e32 v32, v52, v32
	ds_write_b128 v82, v[44:47] offset:36864
	s_waitcnt vmcnt(1)
	ds_write_b16 v68, v64 offset:55808
	ds_write_b16_d16_hi v68, v64 offset:56584
	ds_write_b16 v68, v65 offset:57360
	ds_write_b16_d16_hi v68, v65 offset:58136
	ds_write_b16 v68, v66 offset:58912
	ds_write_b16_d16_hi v68, v66 offset:59688
	ds_write_b16 v68, v67 offset:60464
	ds_write_b16_d16_hi v68, v67 offset:61240
	v_lshlrev_b32_e32 v44, 16, v35
	v_and_b32_e32 v45, 0xffff0000, v35
	v_pk_mul_f32 v[34:35], v[48:49], v[48:49]
	v_add_f32_e32 v32, v53, v32
	v_add_f32_e32 v32, v34, v32
	v_pk_mul_f32 v[46:47], v[44:45], v[44:45]
	v_add_f32_e32 v32, v35, v32
	v_add_f32_e32 v32, v46, v32
	v_add_f32_e32 v32, v47, v32
	ds_bpermute_b32 v33, v92, v32
	v_and_b32_e32 v67, 0xffff0000, v31
	v_lshlrev_b32_e32 v66, 16, v31
	v_mov_b32_e32 v70, v67
	v_pk_mul_f32 v[70:71], v[70:71], v[70:71]
	s_waitcnt lgkmcnt(0)
; __device__ __forceinline__ void attn_unit(LAS unsigned char* lds, const Args& a, int layer, int b, int nb, int kh, float shift2) {
;     ...
;     for (int r = 0; r < 6; ++r) {
;         const int key = (tid >> 3) + 64 * r;
;         const u32x4 kr = kraw[r], vr = vraw[r];
;         float kf[8] = {bflo(kr.x), bfhi(kr.x), bflo(kr.y), bfhi(kr.y), bflo(kr.z), bfhi(kr.z), bflo(kr.w), bfhi(kr.w)};
;         float ss = 0.f;
; #pragma unroll
;         for (int e = 0; e < 8; ++e) ss += kf[e] * kf[e];
;         ss += __shfl_xor(ss, 1); ss += __shfl_xor(ss, 2); ss += __shfl_xor(ss, 4);
;         const float sc = __builtin_amdgcn_rsqf(ss * (1.0f / 64.0f) + EPS);
;         u32x4 o; o.x = pk2(kf[0] * sc * kg0[0], kf[1] * sc * kg0[1]); o.y = pk2(kf[2] * sc * kg0[2], kf[3] * sc * kg0[3]);
;         o.z = pk2(kf[4] * sc * kg1[0], kf[5] * sc * kg1[1]); o.w = pk2(kf[6] * sc * kg1[2], kf[7] * sc * kg1[3]);
;         *(LAS u32x4*)(KS + key * KS_LD + part * 8) = o;
;         LAS bf16_t* vp = VT + (part * 8) * VT_LD + key;
;         vp[0 * VT_LD] = (bf16_t)(vr.x & 0xffffu); vp[1 * VT_LD] = (bf16_t)(vr.x >> 16);
;         vp[2 * VT_LD] = (bf16_t)(vr.y & 0xffffu); vp[3 * VT_LD] = (bf16_t)(vr.y >> 16);
;         vp[4 * VT_LD] = (bf16_t)(vr.z & 0xffffu); vp[5 * VT_LD] = (bf16_t)(vr.z >> 16);
;         vp[6 * VT_LD] = (bf16_t)(vr.w & 0xffffu); vp[7 * VT_LD] = (bf16_t)(vr.w >> 16);
;     }
;     __syncthreads();
;     const float slope2 = ex2(-(float)(hq + 1)) * LOG2E;
;     const float sinkterm = ex2(a.sink[layer * 8 + hq] * LOG2E - shift2);
;     bf16x8 qf[2][4];
; #pragma unroll
;     for (int qt = 0; qt < 2; ++qt) {
;         u32x4 qr[4]; float ss = 0.f;
; #pragma unroll
;         for (int ks = 0; ks < 4; ++ks) { qr[ks] = qraw[qt][ks];
; #pragma unroll
;             for (int e = 0; e < 4; ++e) { const float lo = bflo(qr[ks][e]), hh = bfhi(qr[ks][e]); ss += lo * lo + hh * hh; } }
;         ss += __shfl_xor(ss, 32);
;         const float sc = __builtin_amdgcn_rsqf(ss * (1.0f / 64.0f) + EPS) * (0.125f * LOG2E);
; #pragma unroll
;         for (int ks = 0; ks < 4; ++ks) {
;             const f32x4 g0 = *(const f32x4*)(qg + ks * 16 + hi * 8), g1 = *(const f32x4*)(qg + ks * 16 + hi * 8 + 4);
;             u32x4 o; o.x = pk2(bflo(qr[ks].x) * sc * g0[0], bfhi(qr[ks].x) * sc * g0[1]); o.y = pk2(bflo(qr[ks].y) * sc * g0[2], bfhi(qr[ks].y) * sc * g0[3]);
	v_add_f32_e32 v32, v32, v33
	ds_bpermute_b32 v33, v93, v32
	v_add_f32_e32 v65, v108, v109
	v_add_f32_e32 v16, v65, v16
	v_add_f32_e32 v16, v17, v16
	v_add_f32_e32 v17, v102, v103
	s_waitcnt lgkmcnt(0)
	v_add_f32_e32 v32, v32, v33
	ds_bpermute_b32 v33, v94, v32
	v_pk_mul_f32 v[92:93], v[86:87], v[86:87]
	v_add_f32_e32 v16, v17, v16
	v_add_f32_e32 v17, v22, v23
	v_add_f32_e32 v16, v17, v16
	s_waitcnt lgkmcnt(0)
	v_add_f32_e32 v32, v32, v33
	v_fmamk_f32 v32, v32, 0x3c800000, v239
	v_rsq_f32_e32 v46, v32
	v_add_f32_e32 v17, v92, v93
	v_add_f32_e32 v16, v17, v16
	v_lshlrev_b32_e32 v92, 16, v1
	v_pk_mul_f32 v[32:33], v[46:47], v[54:55] op_sel_hi:[0,1]
	v_pk_mul_f32 v[34:35], v[46:47], v[50:51] op_sel_hi:[0,1]
	v_pk_mul_f32 v[32:33], v[40:41], v[32:33]
	v_pk_mul_f32 v[34:35], v[42:43], v[34:35]
	v_cvt_pk_bf16_f32 v32, v32, v33
	v_cvt_pk_bf16_f32 v33, v34, v35
	v_pk_mul_f32 v[34:35], v[46:47], v[48:49] op_sel_hi:[0,1]
	v_pk_mul_f32 v[34:35], v[36:37], v[34:35]
	v_pk_mul_f32 v[36:37], v[46:47], v[44:45] op_sel_hi:[0,1]
	v_pk_mul_f32 v[36:37], v[38:39], v[36:37]
	v_cvt_pk_bf16_f32 v34, v34, v35
	v_cvt_pk_bf16_f32 v35, v36, v37
	ds_write_b128 v82, v[32:35] offset:46080
	s_waitcnt vmcnt(0)
	ds_write_b16 v68, v60 offset:55936
	ds_write_b16_d16_hi v68, v60 offset:56712
	ds_write_b16 v68, v61 offset:57488
	ds_write_b16_d16_hi v68, v61 offset:58264
	ds_write_b16 v68, v62 offset:59040
	ds_write_b16_d16_hi v68, v62 offset:59816
	ds_write_b16 v68, v63 offset:60592
	ds_write_b16_d16_hi v68, v63 offset:61368
	v_add_u32_e32 v32, 1, v97
	v_cvt_f32_i32_e32 v32, v32
	v_lshlrev_b32_e32 v36, 5, v96
	s_waitcnt lgkmcnt(0)
	s_barrier
	v_exp_f32_e64 v64, -v32
	v_lshl_add_u32 v32, s14, 3, v97
	v_ashrrev_i32_e32 v33, 31, v32
	v_lshl_add_u64 v[32:33], v[32:33], 2, s[74:75]
	global_load_dword v187, v[32:33], off
	global_load_dwordx4 v[56:59], v36, s[10:11] offset:16
	global_load_dwordx4 v[60:63], v36, s[10:11]
	global_load_dwordx4 v[48:51], v36, s[10:11] offset:80
	global_load_dwordx4 v[52:55], v36, s[10:11] offset:64
	global_load_dwordx4 v[40:43], v36, s[10:11] offset:144
	global_load_dwordx4 v[44:47], v36, s[10:11] offset:128
	global_load_dwordx4 v[32:35], v36, s[10:11] offset:208
	s_nop 0
	global_load_dwordx4 v[36:39], v36, s[10:11] offset:192
	v_lshlrev_b32_e32 v68, 16, v30
	v_mov_b32_e32 v30, v66
	v_mov_b32_e32 v31, v68
	v_pk_fma_f32 v[30:31], v[30:31], v[30:31], v[70:71]
	v_and_b32_e32 v71, 0xffff0000, v29
	v_lshlrev_b32_e32 v70, 16, v29
	v_mov_b32_e32 v74, v71
	v_mov_b32_e32 v28, v70
	v_mov_b32_e32 v29, v72
	v_pk_mul_f32 v[74:75], v[74:75], v[74:75]
	v_and_b32_e32 v93, 0xffff0000, v1
	v_pk_fma_f32 v[28:29], v[28:29], v[28:29], v[74:75]
	v_and_b32_e32 v75, 0xffff0000, v27
	v_lshlrev_b32_e32 v74, 16, v27
	v_mov_b32_e32 v78, v75
	v_mov_b32_e32 v26, v74
	v_mov_b32_e32 v27, v76
	v_pk_mul_f32 v[78:79], v[78:79], v[78:79]
	v_and_b32_e32 v23, 0xffff0000, v12
	v_pk_fma_f32 v[26:27], v[26:27], v[26:27], v[78:79]
	v_lshlrev_b32_e32 v78, 16, v25
	v_and_b32_e32 v79, 0xffff0000, v25
	v_pk_mul_f32 v[24:25], v[84:85], v[84:85]
	v_pk_mul_f32 v[82:83], v[78:79], v[78:79]
	v_add_f32_e32 v17, v24, v25
	v_add_f32_e32 v16, v17, v16
	v_add_f32_e32 v17, v82, v83
	v_add_f32_e32 v16, v17, v16
	v_add_f32_e32 v16, v27, v16
	v_add_f32_e32 v16, v26, v16
	v_add_f32_e32 v16, v29, v16
	v_add_f32_e32 v16, v28, v16
	v_add_f32_e32 v16, v31, v16
	v_add_f32_e32 v16, v30, v16
	ds_bpermute_b32 v17, v185, v16
	v_lshlrev_b32_e32 v82, 16, v3
	v_and_b32_e32 v83, 0xffff0000, v3
	v_lshlrev_b32_e32 v22, 16, v12
	v_mov_b32_e32 v25, v23
	s_waitcnt lgkmcnt(0)
	v_add_f32_e32 v16, v16, v17
	v_fmamk_f32 v16, v16, 0x3c800000, v239
	v_rsq_f32_e32 v16, v16
	v_and_b32_e32 v27, 0xffff0000, v10
	v_lshlrev_b32_e32 v26, 16, v10
	v_mov_b32_e32 v29, v27
	v_mul_f32_e32 v16, 0x3e38aa3b, v16
	v_pk_mul_f32 v[18:19], v[16:17], v[116:117] op_sel_hi:[0,1]
	v_mul_f32_e32 v189, 0x3fb8aa3b, v64
	v_xor_b32_e32 v64, 0x80000000, v186
	s_waitcnt vmcnt(6)
	v_pk_mul_f32 v[18:19], v[60:61], v[18:19]
	s_nop 0
	v_cvt_pk_bf16_f32 v112, v18, v19
	v_pk_mul_f32 v[18:19], v[16:17], v[114:115] op_sel_hi:[0,1]
	v_pk_mul_f32 v[18:19], v[62:63], v[18:19]
	s_nop 0
	v_cvt_pk_bf16_f32 v113, v18, v19
	v_pk_mul_f32 v[18:19], v[16:17], v[110:111] op_sel_hi:[0,1]
	v_pk_mul_f32 v[18:19], v[56:57], v[18:19]
	s_nop 0
	v_cvt_pk_bf16_f32 v114, v18, v19
	v_pk_mul_f32 v[18:19], v[16:17], v[106:107] op_sel_hi:[0,1]
	v_pk_mul_f32 v[18:19], v[58:59], v[18:19]
	s_nop 0
	v_cvt_pk_bf16_f32 v115, v18, v19
	v_pk_mul_f32 v[18:19], v[16:17], v[104:105] op_sel_hi:[0,1]
	s_waitcnt vmcnt(4)
	v_pk_mul_f32 v[18:19], v[52:53], v[18:19]
	s_nop 0
	v_cvt_pk_bf16_f32 v116, v18, v19
	v_pk_mul_f32 v[18:19], v[16:17], v[100:101] op_sel_hi:[0,1]
	v_pk_mul_f32 v[18:19], v[54:55], v[18:19]
	v_lshlrev_b32_e32 v100, 16, v0
	v_cvt_pk_bf16_f32 v117, v18, v19
	v_pk_mul_f32 v[18:19], v[16:17], v[98:99] op_sel_hi:[0,1]
	v_pk_mul_f32 v[18:19], v[48:49], v[18:19]
	v_and_b32_e32 v101, 0xffff0000, v0
	v_cvt_pk_bf16_f32 v118, v18, v19
	v_pk_mul_f32 v[18:19], v[16:17], v[86:87] op_sel_hi:[0,1]
	v_pk_mul_f32 v[18:19], v[50:51], v[18:19]
	v_lshlrev_b32_e32 v86, 16, v2
	v_cvt_pk_bf16_f32 v119, v18, v19
	v_pk_mul_f32 v[18:19], v[16:17], v[84:85] op_sel_hi:[0,1]
	s_waitcnt vmcnt(2)
	v_pk_mul_f32 v[18:19], v[44:45], v[18:19]
	v_and_b32_e32 v87, 0xffff0000, v2
	v_cvt_pk_bf16_f32 v120, v18, v19
	v_pk_mul_f32 v[18:19], v[16:17], v[78:79] op_sel_hi:[0,1]
	v_pk_mul_f32 v[18:19], v[46:47], v[18:19]
	v_pk_mul_f32 v[98:99], v[92:93], v[92:93]
	v_cvt_pk_bf16_f32 v121, v18, v19
	v_pk_mul_f32 v[18:19], v[16:17], v[76:77] op_sel_hi:[0,1]
	v_pk_mul_f32 v[18:19], v[18:19], v[40:41]
	v_pk_mul_f32 v[0:1], v[100:101], v[100:101]
	v_cvt_pk_bf16_f32 v122, v18, v19
	v_pk_mul_f32 v[18:19], v[16:17], v[74:75] op_sel_hi:[0,1]
	v_pk_mul_f32 v[18:19], v[18:19], v[42:43]
	v_pk_mul_f32 v[2:3], v[86:87], v[86:87]
	v_cvt_pk_bf16_f32 v123, v18, v19
	v_pk_mul_f32 v[18:19], v[16:17], v[72:73] op_sel_hi:[0,1]
	s_waitcnt vmcnt(0)
; __device__ __forceinline__ unsigned pk2(float lo, float hi) { f32x2 v = {lo, hi}; bf2_t b = __builtin_convertvector(v, bf2_t); return __builtin_bit_cast(unsigned, b); }
; __device__ __forceinline__ void attn_unit(LAS unsigned char* lds, const Args& a, int layer, int b, int nb, int kh, float shift2) {
;     ...
;     bf16x8 qf[2][4];
; #pragma unroll
;     for (int qt = 0; qt < 2; ++qt) {
;         u32x4 qr[4]; float ss = 0.f;
; #pragma unroll
;         for (int ks = 0; ks < 4; ++ks) { qr[ks] = qraw[qt][ks];
; #pragma unroll
;             for (int e = 0; e < 4; ++e) { const float lo = bflo(qr[ks][e]), hh = bfhi(qr[ks][e]); ss += lo * lo + hh * hh; } }
;         ss += __shfl_xor(ss, 32);
;         const float sc = __builtin_amdgcn_rsqf(ss * (1.0f / 64.0f) + EPS) * (0.125f * LOG2E);
; #pragma unroll
;         for (int ks = 0; ks < 4; ++ks) {
;             const f32x4 g0 = *(const f32x4*)(qg + ks * 16 + hi * 8), g1 = *(const f32x4*)(qg + ks * 16 + hi * 8 + 4);
;             u32x4 o; o.x = pk2(bflo(qr[ks].x) * sc * g0[0], bfhi(qr[ks].x) * sc * g0[1]); o.y = pk2(bflo(qr[ks].y) * sc * g0[2], bfhi(qr[ks].y) * sc * g0[3]);
;             o.z = pk2(bflo(qr[ks].z) * sc * g1[0], bfhi(qr[ks].z) * sc * g1[1]); o.w = pk2(bflo(qr[ks].w) * sc * g1[2], bfhi(qr[ks].w) * sc * g1[3]);
;             qf[qt][ks] = __builtin_bit_cast(bf16x8, o);
;         }
;     }
;     f32x16 oa0, oa1, ob0, ob1; float la = 0.f, lb = 0.f;
; #pragma unroll
;     for (int e = 0; e < 16; ++e) { oa0[e] = 0.f; oa1[e] = 0.f; ob0[e] = 0.f; ob1[e] = 0.f; }
;     const int kt0 = ib >> 5;
;     const float nshift = -shift2;
; #pragma unroll 1
;     for (int kt = kt0; kt <= kt0 + 9; ++kt) {
;         const int gb = nb - 1 + (kt >> 2);
;         if (gb < 0 || gb >= SEQ / 128) continue;
;         f32x16 sa, sb;
; #pragma unroll
;         for (int e = 0; e < 16; ++e) { sa[e] = nshift; sb[e] = nshift; }
	v_pk_mul_f32 v[18:19], v[18:19], v[36:37]
	v_add_f32_e32 v81, v98, v99
	v_cvt_pk_bf16_f32 v124, v18, v19
	v_pk_mul_f32 v[18:19], v[16:17], v[70:71] op_sel_hi:[0,1]
	v_pk_mul_f32 v[18:19], v[18:19], v[38:39]
	v_add_f32_e32 v0, v0, v1
	v_cvt_pk_bf16_f32 v125, v18, v19
	v_pk_mul_f32 v[18:19], v[16:17], v[68:69] op_sel_hi:[0,1]
	v_pk_mul_f32 v[16:17], v[16:17], v[66:67] op_sel_hi:[0,1]
	v_pk_mul_f32 v[18:19], v[18:19], v[32:33]
	v_pk_mul_f32 v[16:17], v[16:17], v[34:35]
	v_cvt_pk_bf16_f32 v126, v18, v19
	v_cvt_pk_bf16_f32 v127, v16, v17
	v_and_b32_e32 v17, 0xffff0000, v15
	v_and_b32_e32 v19, 0xffff0000, v14
	v_lshlrev_b32_e32 v16, 16, v15
	v_lshlrev_b32_e32 v18, 16, v14
	v_mov_b32_e32 v20, v17
	v_mov_b32_e32 v21, v19
	v_mov_b32_e32 v14, v16
	v_mov_b32_e32 v15, v18
	v_pk_mul_f32 v[20:21], v[20:21], v[20:21]
	v_lshlrev_b32_e32 v78, 16, v4
	v_pk_fma_f32 v[14:15], v[14:15], v[14:15], v[20:21]
	v_and_b32_e32 v21, 0xffff0000, v13
	v_lshlrev_b32_e32 v20, 16, v13
	v_mov_b32_e32 v24, v21
	v_and_b32_e32 v79, 0xffff0000, v4
	v_pk_mul_f32 v[84:85], v[82:83], v[82:83]
	v_add_f32_e32 v0, v0, v81
	v_add_f32_e32 v1, v2, v3
	v_mov_b32_e32 v12, v20
	v_mov_b32_e32 v13, v22
	v_pk_mul_f32 v[24:25], v[24:25], v[24:25]
	v_lshlrev_b32_e32 v74, 16, v5
	v_and_b32_e32 v75, 0xffff0000, v5
	v_pk_mul_f32 v[4:5], v[78:79], v[78:79]
	v_add_f32_e32 v65, v84, v85
	v_add_f32_e32 v0, v1, v0
	v_pk_fma_f32 v[12:13], v[12:13], v[12:13], v[24:25]
	v_and_b32_e32 v25, 0xffff0000, v11
	v_lshlrev_b32_e32 v72, 16, v6
	v_and_b32_e32 v73, 0xffff0000, v6
	v_pk_mul_f32 v[76:77], v[74:75], v[74:75]
	v_add_f32_e32 v0, v65, v0
	v_add_f32_e32 v1, v4, v5
	v_lshlrev_b32_e32 v24, 16, v11
	v_mov_b32_e32 v28, v25
	v_lshlrev_b32_e32 v68, 16, v7
	v_and_b32_e32 v69, 0xffff0000, v7
	v_pk_mul_f32 v[6:7], v[72:73], v[72:73]
	v_add_f32_e32 v0, v1, v0
	v_add_f32_e32 v1, v76, v77
	v_mov_b32_e32 v10, v24
	v_mov_b32_e32 v11, v26
	v_pk_mul_f32 v[28:29], v[28:29], v[28:29]
	v_lshlrev_b32_e32 v66, 16, v8
	v_and_b32_e32 v67, 0xffff0000, v8
	v_pk_mul_f32 v[70:71], v[68:69], v[68:69]
	v_add_f32_e32 v0, v1, v0
	v_add_f32_e32 v1, v6, v7
	v_pk_fma_f32 v[10:11], v[10:11], v[10:11], v[28:29]
	v_lshlrev_b32_e32 v28, 16, v9
	v_and_b32_e32 v29, 0xffff0000, v9
	v_pk_mul_f32 v[8:9], v[66:67], v[66:67]
	v_add_f32_e32 v0, v1, v0
	v_add_f32_e32 v1, v70, v71
	v_pk_mul_f32 v[30:31], v[28:29], v[28:29]
	v_add_f32_e32 v0, v1, v0
	v_add_f32_e32 v1, v8, v9
	v_add_f32_e32 v0, v1, v0
	v_add_f32_e32 v1, v30, v31
	v_add_f32_e32 v0, v1, v0
	v_add_f32_e32 v0, v11, v0
	v_add_f32_e32 v0, v10, v0
	v_add_f32_e32 v0, v13, v0
	v_add_f32_e32 v0, v12, v0
	v_add_f32_e32 v0, v15, v0
	v_add_f32_e32 v0, v14, v0
	ds_bpermute_b32 v1, v185, v0
	v_mov_b32_e32 v30, v201
	v_mov_b32_e32 v31, v201
	v_mov_b32_e32 v65, v64
	v_mov_b32_e32 v70, v64
	s_waitcnt lgkmcnt(0)
	v_add_f32_e32 v0, v0, v1
	v_fmamk_f32 v0, v0, 0x3c800000, v239
	v_rsq_f32_e32 v0, v0
	v_mov_b32_e32 v71, v64
	v_mov_b32_e32 v76, v64
	v_mov_b32_e32 v77, v64
	v_mul_f32_e32 v0, 0x3e38aa3b, v0
	v_pk_mul_f32 v[2:3], v[0:1], v[100:101] op_sel_hi:[0,1]
	v_pk_mul_f32 v[2:3], v[60:61], v[2:3]
	s_nop 0
	v_cvt_pk_bf16_f32 v128, v2, v3
	v_pk_mul_f32 v[2:3], v[0:1], v[92:93] op_sel_hi:[0,1]
	v_pk_mul_f32 v[2:3], v[62:63], v[2:3]
	s_nop 0
	v_cvt_pk_bf16_f32 v129, v2, v3
	v_pk_mul_f32 v[2:3], v[0:1], v[86:87] op_sel_hi:[0,1]
	v_pk_mul_f32 v[2:3], v[56:57], v[2:3]
	s_nop 0
	v_cvt_pk_bf16_f32 v130, v2, v3
	v_pk_mul_f32 v[2:3], v[0:1], v[82:83] op_sel_hi:[0,1]
	v_pk_mul_f32 v[2:3], v[58:59], v[2:3]
	s_nop 0
	v_cvt_pk_bf16_f32 v131, v2, v3
	v_pk_mul_f32 v[2:3], v[0:1], v[78:79] op_sel_hi:[0,1]
	v_pk_mul_f32 v[2:3], v[52:53], v[2:3]
	v_mov_b32_e32 v78, v64
	v_cvt_pk_bf16_f32 v132, v2, v3
	v_pk_mul_f32 v[2:3], v[0:1], v[74:75] op_sel_hi:[0,1]
	v_pk_mul_f32 v[2:3], v[54:55], v[2:3]
	v_mov_b32_e32 v74, v64
	v_cvt_pk_bf16_f32 v133, v2, v3
	v_pk_mul_f32 v[2:3], v[0:1], v[72:73] op_sel_hi:[0,1]
	v_pk_mul_f32 v[2:3], v[48:49], v[2:3]
	v_mov_b32_e32 v72, v64
	v_cvt_pk_bf16_f32 v134, v2, v3
	v_pk_mul_f32 v[2:3], v[0:1], v[68:69] op_sel_hi:[0,1]
	v_pk_mul_f32 v[2:3], v[50:51], v[2:3]
	v_mov_b32_e32 v68, v64
	v_cvt_pk_bf16_f32 v135, v2, v3
	v_pk_mul_f32 v[2:3], v[0:1], v[66:67] op_sel_hi:[0,1]
	v_pk_mul_f32 v[2:3], v[44:45], v[2:3]
	v_mov_b32_e32 v66, v64
	v_cvt_pk_bf16_f32 v136, v2, v3
	v_pk_mul_f32 v[2:3], v[0:1], v[28:29] op_sel_hi:[0,1]
	v_pk_mul_f32 v[2:3], v[46:47], v[2:3]
	v_mov_b32_e32 v28, v201
	v_cvt_pk_bf16_f32 v137, v2, v3
	v_pk_mul_f32 v[2:3], v[0:1], v[26:27] op_sel_hi:[0,1]
	v_pk_mul_f32 v[2:3], v[40:41], v[2:3]
	v_mov_b32_e32 v26, v201
	v_cvt_pk_bf16_f32 v138, v2, v3
	v_pk_mul_f32 v[2:3], v[0:1], v[24:25] op_sel_hi:[0,1]
	v_pk_mul_f32 v[2:3], v[42:43], v[2:3]
	v_mov_b32_e32 v24, v201
	v_cvt_pk_bf16_f32 v139, v2, v3
	v_pk_mul_f32 v[2:3], v[0:1], v[22:23] op_sel_hi:[0,1]
	v_pk_mul_f32 v[2:3], v[36:37], v[2:3]
	v_mov_b32_e32 v22, v201
	v_cvt_pk_bf16_f32 v140, v2, v3
	v_pk_mul_f32 v[2:3], v[0:1], v[20:21] op_sel_hi:[0,1]
	v_pk_mul_f32 v[2:3], v[38:39], v[2:3]
	v_mov_b32_e32 v20, v201
	v_cvt_pk_bf16_f32 v141, v2, v3
	v_pk_mul_f32 v[2:3], v[0:1], v[18:19] op_sel_hi:[0,1]
	v_pk_mul_f32 v[2:3], v[32:33], v[2:3]
	v_pk_mul_f32 v[0:1], v[0:1], v[16:17] op_sel_hi:[0,1]
	v_cvt_pk_bf16_f32 v142, v2, v3
	v_pk_mul_f32 v[0:1], v[34:35], v[0:1]
	v_bfe_u32 v2, v89, 6, 1
	v_cvt_pk_bf16_f32 v143, v0, v1
	v_mul_u32_u24_e32 v1, 0x308, v91
	v_lshlrev_b32_e32 v3, 7, v2
	v_add3_u32 v193, v1, v3, v95
	v_mul_u32_u24_e32 v1, 0x2400, v2
	v_mul_u32_u24_e32 v2, 0x90, v91
	v_and_b32_e32 v0, 0x5f, v89
	v_add3_u32 v194, v1, v2, v80
	v_or3_b32 v1, v90, v188, s1
	v_mov_b32_e32 v16, v201
	v_mov_b32_e32 v17, v201
	v_sub_u32_e32 v195, v1, v0
	v_mov_b32_e32 v18, v201
	v_mov_b32_e32 v19, v201
	v_mov_b32_e32 v21, v201
	v_mov_b32_e32 v23, v201
	v_mov_b32_e32 v25, v201
	v_mov_b32_e32 v27, v201
	v_mov_b32_e32 v29, v201
	v_mov_b64_e32 v[62:63], v[30:31]
	v_mov_b64_e32 v[46:47], v[30:31]
	v_mov_b64_e32 v[0:1], v[16:17]
	v_mov_b32_e32 v67, v64
	v_mov_b32_e32 v69, v64
	v_mov_b32_e32 v73, v64
	v_mov_b32_e32 v75, v64
	v_mov_b32_e32 v79, v64
	v_mov_b64_e32 v[60:61], v[28:29]
	v_mov_b64_e32 v[58:59], v[26:27]
	v_mov_b64_e32 v[56:57], v[24:25]
	v_mov_b64_e32 v[54:55], v[22:23]
	v_mov_b64_e32 v[52:53], v[20:21]
	v_mov_b64_e32 v[50:51], v[18:19]
	v_mov_b64_e32 v[48:49], v[16:17]
	v_mov_b64_e32 v[44:45], v[28:29]
	v_mov_b64_e32 v[42:43], v[26:27]
	v_mov_b64_e32 v[40:41], v[24:25]
	v_mov_b64_e32 v[38:39], v[22:23]
	v_mov_b64_e32 v[36:37], v[20:21]
	v_mov_b64_e32 v[34:35], v[18:19]
	v_mov_b64_e32 v[32:33], v[16:17]
	v_mov_b64_e32 v[2:3], v[18:19]
	v_mov_b64_e32 v[4:5], v[20:21]
	v_mov_b64_e32 v[6:7], v[22:23]
	v_mov_b64_e32 v[8:9], v[24:25]
	v_mov_b64_e32 v[10:11], v[26:27]
	v_mov_b64_e32 v[12:13], v[28:29]
	v_mov_b64_e32 v[14:15], v[30:31]
	s_branch .LBB0_445

; __device__ __forceinline__ unsigned xb_ld(unsigned* p)              { return __hip_atomic_load(p, __ATOMIC_RELAXED, __HIP_MEMORY_SCOPE_AGENT); }
; __device__ __forceinline__ unsigned xb_add(unsigned* p, unsigned v) { return __hip_atomic_fetch_add(p, v, __ATOMIC_RELAXED, __HIP_MEMORY_SCOPE_AGENT); }
; #define XB_SPIN(cond, bar) do { unsigned _sp = 0; while (cond) { __builtin_amdgcn_s_sleep(1); \
;     if ((++_sp & 255u) == 0u) { if (xb_ld(&(bar)[XB_TMO])) break; if (_sp > XB_SPIN_CAP) { atomicAdd(&(bar)[XB_TMO], 1u); break; } } } } while (0)
; __device__ __forceinline__ void xcd_barrier(const XcdBarrier& b) {
;     asm volatile("s_waitcnt vmcnt(0)" ::: "memory");
;     __syncthreads();
;     if (threadIdx.x == 0) {
;         unsigned* bar = b.bar;
;         __builtin_amdgcn_s_waitcnt(0);
;         unsigned nloc = b.st[0], nx = b.st[1];
;         if (nloc == 0u) { xcd_barrier_complete(bar, b.x, nloc, nx); b.st[0] = nloc; b.st[1] = nx; }
;         const unsigned old = xb_add(&bar[XB_XSUB(b.x)], 1u);
;         const unsigned gen = old / nloc;
;         if (old + 1u == (gen + 1u) * nloc) {
;             __builtin_amdgcn_fence(__ATOMIC_RELEASE, "agent");
;             asm volatile("s_waitcnt vmcnt(0)" ::: "memory");
;             const unsigned og = xb_add(&bar[XB_TOP], 1u);
;             const unsigned tg = og / nx;
;             __builtin_amdgcn_fence(__ATOMIC_ACQUIRE, "agent");
;             if (og + 1u == (tg + 1u) * nx) xb_add(&bar[XB_TOPGEN], 1u);
;             else XB_SPIN(xb_ld(&bar[XB_TOPGEN]) == tg, bar);
;             xb_add(&bar[XB_XGEN(b.x)], 1u);
;             asm volatile("s_waitcnt vmcnt(0)" ::: "memory");
;         } else {
;             __builtin_amdgcn_fence(__ATOMIC_ACQUIRE, "agent");
;             XB_SPIN(xb_ld(&bar[XB_XGEN(b.x)]) == gen, bar);
;             asm volatile("s_waitcnt vmcnt(0)" ::: "memory");
;         }
;     }
;     __syncthreads();
; }
.LBB0_554:
	s_waitcnt vmcnt(0)
	s_waitcnt vmcnt(0)
	s_barrier
	s_mov_b64 s[10:11], exec
	v_readlane_b32 s8, v253, 41
	v_readlane_b32 s9, v253, 42
	v_readlane_b32 s64, v255, 3
	v_readlane_b32 s66, v255, 5
	v_readlane_b32 s68, v255, 7
	v_readlane_b32 s70, v255, 9
	v_readlane_b32 s72, v255, 11
	v_readlane_b32 s74, v255, 13
	v_readlane_b32 s76, v255, 15
	v_readlane_b32 s78, v255, 17
	v_readlane_b32 s84, v255, 19
	v_readlane_b32 s12, v255, 28
	s_and_b64 s[8:9], s[10:11], s[8:9]
	v_readlane_b32 s65, v255, 4
	v_readlane_b32 s67, v255, 6
	v_readlane_b32 s69, v255, 8
	v_readlane_b32 s71, v255, 10
	v_readlane_b32 s73, v255, 12
	v_readlane_b32 s75, v255, 14
	v_readlane_b32 s77, v255, 16
	v_readlane_b32 s79, v255, 18
	v_readlane_b32 s85, v255, 20
	v_readlane_b32 s14, v255, 30
	v_readlane_b32 s13, v255, 29
	v_readlane_b32 s15, v255, 31
	s_mov_b64 exec, s[8:9]
	s_cbranch_execz .LBB0_606
	s_waitcnt vmcnt(0) lgkmcnt(0)
	v_readlane_b32 s22, v255, 54
	v_readlane_b32 s24, v254, 51
	v_readlane_b32 s8, v254, 25
	v_readlane_b32 s9, v254, 26
	v_readlane_b32 s20, v254, 27
	v_readlane_b32 s21, v254, 28
	s_add_u32 s22, s22, 1
	v_mov_b32_e32 v0, s24
	ds_read_b32 v2, v0
	s_add_u32 s8, s8, 0x2c00
	s_addc_u32 s9, s9, 0
	s_add_u32 s20, s20, 0x2c00
	s_addc_u32 s21, s21, 0
	v_writelane_b32 v255, s22, 54
	v_mov_b32_e32 v1, 1
	v_mov_b32_e32 v3, 0
	s_nop 1
	global_atomic_add v4, v3, v1, s[8:9] sc0
	s_waitcnt vmcnt(0) lgkmcnt(0)
	v_readfirstlane_b32 s24, v4
	v_readfirstlane_b32 s23, v2
	s_add_u32 s24, s24, 1
	s_mul_i32 s25, s23, s22
	s_cmp_lg_u32 s24, s25
	s_cbranch_scc1 .Lgd_notlast_1
	buffer_wbl2 sc1
	s_waitcnt vmcnt(0)
	v_readlane_b32 s8, v254, 29
	v_readlane_b32 s9, v254, 30
	v_mov_b32_e32 v5, s23
	s_add_u32 s8, s8, 0x1c00
	s_addc_u32 s9, s9, 0
	s_nop 4
	global_atomic_add v3, v5, s[8:9]
	global_atomic_add v3, v5, s[8:9] offset:256
	global_atomic_add v3, v5, s[8:9] offset:512
	global_atomic_add v3, v5, s[8:9] offset:768
	global_atomic_add v3, v5, s[8:9] offset:1024
	global_atomic_add v3, v5, s[8:9] offset:1280
	global_atomic_add v3, v5, s[8:9] offset:1536
	global_atomic_add v3, v5, s[8:9] offset:1792
	global_atomic_add v3, v5, s[8:9] offset:2048
	global_atomic_add v3, v5, s[8:9] offset:2304
	global_atomic_add v3, v5, s[8:9] offset:2560
	global_atomic_add v3, v5, s[8:9] offset:2816
	global_atomic_add v3, v5, s[8:9] offset:3072
	global_atomic_add v3, v5, s[8:9] offset:3328
	global_atomic_add v3, v5, s[8:9] offset:3584
	global_atomic_add v3, v5, s[8:9] offset:3840

; template <class Epi, class Sched, bool ALIGN_EPI = true, bool SP2 = true, class Pre = NoPre>
; __device__ __forceinline__ void gemm_phase(LAS unsigned char* lds, const Gemm g, const Sched& S, const Epi& E, const Pre& pre = Pre()) {
;     ...
;     const int tid = tid_, wid = __builtin_amdgcn_readfirstlane(tid >> 6), lane = tid & 63, wr = wid >> 2, wc = wid & 3, fr = lane & 15, fq = lane >> 4;
;     const int nt = g.K / BK;
;     unsigned voffA[2], voffB[2];
; #pragma unroll
;     for (int i = 0; i < 2; ++i) { int R, C; stage_rc(tid * 16 + i * 8192, R, C); const int Rb = Epi::PERM ? ((R & ~31) + perm32(R & 31)) : R;
;         voffA[i] = (unsigned)(R * g.lda + C) * 2u; voffB[i] = (unsigned)(Rb * g.ldb + C) * 2u; }
;     const size_t kstep = (size_t)(BK * 2);
;     const size_t hsA = (size_t)HALF * g.lda * 2, hsB = (size_t)HALF * g.ldb * 2;
;     const unsigned ldsw = (unsigned)wid * 1024u;
;     const int aoff = lds_byte(wr * 64 + fr, fq * 8), boff = lds_byte(wc * 32 + fr, fq * 8);
;     ...
;     Unit cur, nxt; int ui = 0;
;     if (!S.next(0, cur)) return;
;     f32x4 acc[2][2][4][2];
; #pragma unroll
;     for (int a = 0; a < 2; ++a)
; #pragma unroll
;         for (int b = 0; b < 2; ++b)
; #pragma unroll
;             for (int m = 0; m < 4; ++m)
; #pragma unroll
;                 for (int n = 0; n < 2; ++n) acc[a][b][m][n] = (f32x4){0.f, 0.f, 0.f, 0.f};
;     bf16x8 At[4][2], B0[2][2], B1[2][2];
;     const char* cA = PG8_TILE_A(cur); const char* cB = PG8_TILE_B(cur);
;     if constexpr (SP2) {
;         PG8_STAGE(PG8_SB(0, 0), cB, voffB); PG8_STAGE(PG8_SB(0, 1), cB + hsB, voffB); PG8_STAGE(PG8_SA(0, 0), cA, voffA); PG8_STAGE(PG8_SA(0, 1), cA + hsA, voffA);
;         pre();
;         if (wr == 1) PG8_BAR;
;         PG8_WAIT_V(2); PG8_BAR;
;         PG8_STAGE(PG8_SB(1, 0), cB + kstep, voffB); PG8_STAGE(PG8_SA(1, 0), cA + kstep, voffA); PG8_STAGE(PG8_SB(1, 1), cB + hsB + kstep, voffB);
; __device__ __forceinline__ void xcd_barrier(const XcdBarrier& b) {
;     asm volatile("s_waitcnt vmcnt(0)" ::: "memory");
;     __syncthreads();
;     if (threadIdx.x == 0) {
;         unsigned* bar = b.bar;
;         __builtin_amdgcn_s_waitcnt(0);
;         unsigned nloc = b.st[0], nx = b.st[1];
;         if (nloc == 0u) { xcd_barrier_complete(bar, b.x, nloc, nx); b.st[0] = nloc; b.st[1] = nx; }
;         const unsigned old = xb_add(&bar[XB_XSUB(b.x)], 1u);
.Lgd_done_1:
	s_waitcnt vmcnt(0)
.LBB0_606:
	s_or_b64 exec, exec, s[10:11]
	s_add_u32 s16, s92, 0xa800000
	s_addc_u32 s17, s93, 0
	s_cmpk_lt_i32 s49, 0x100
	s_cselect_b64 s[8:9], -1, 0
	v_writelane_b32 v255, s8, 45
	v_mov_b32_e32 v6, v236
	s_waitcnt lgkmcnt(0)
	s_barrier
	v_writelane_b32 v255, s9, 46
	s_cmpk_gt_i32 s49, 0xff
	s_nop 0
	v_readfirstlane_b32 s5, v6
	s_cbranch_scc1 .LBB0_626
	v_lshlrev_b32_e32 v3, 4, v6
	v_add_u32_e32 v1, 0x2000, v3
	v_ashrrev_i32_e32 v0, 31, v1
	v_lshrrev_b32_e32 v0, 22, v0
	v_add_u32_e32 v0, v1, v0
	v_ashrrev_i32_e32 v0, 10, v0
	v_mul_i32_i24_e32 v2, 0x400, v0
	v_sub_u32_e32 v1, v1, v2
	v_lshrrev_b32_e32 v2, 4, v1
	v_bitop3_b32 v2, v2, v1, 32 bitop3:0x6c
	v_ashrrev_i32_e32 v1, 31, v2
	v_lshrrev_b32_e32 v1, 26, v1
	v_add_u32_e32 v4, v2, v1
	v_lshlrev_b32_e32 v5, 3, v0
	v_ashrrev_i32_e32 v1, 6, v4
	v_and_b32_e32 v5, -16, v5
	v_add_u32_e32 v5, v1, v5
	v_and_b32_e32 v7, 3, v1
	s_mov_b32 s1, 0x3fffe0
	v_lshrrev_b32_e32 v8, 2, v5
	v_lshlrev_b32_e32 v9, 1, v5
	v_and_b32_e32 v4, 0xc0, v4
	v_and_or_b32 v7, v5, s1, v7
	v_and_b32_e32 v8, 4, v8
	v_and_b32_e32 v9, 24, v9
	v_sub_u32_e32 v2, v2, v4
	v_or3_b32 v7, v7, v8, v9
	v_lshlrev_b32_e32 v8, 5, v0
	v_ashrrev_i16_sdwa v2, v252, sext(v2) dst_sel:DWORD dst_unused:UNUSED_PAD src0_sel:DWORD src1_sel:BYTE_0
	v_and_b32_e32 v8, 32, v8
	v_bfe_i32 v2, v2, 0, 16
	v_add_lshl_u32 v4, v8, v2, 1
	v_lshl_add_u32 v128, v7, 10, v4
	v_lshl_add_u32 v130, v5, 10, v4
	v_bfe_i32 v4, v6, 27, 1
	v_lshrrev_b32_e32 v4, 22, v4
	v_add_u32_e32 v4, v3, v4
	v_and_b32_e32 v4, 0xfffffc00, v4
	v_sub_u32_e32 v3, v3, v4
	v_lshrrev_b32_e32 v4, 4, v3
	v_bitop3_b32 v5, v4, v3, 32 bitop3:0x6c
	v_ashrrev_i32_e32 v4, 31, v6
	v_lshrrev_b32_e32 v4, 26, v4
	v_ashrrev_i32_e32 v3, 31, v5
	v_add_u32_e32 v4, v6, v4
	v_lshrrev_b32_e32 v3, 26, v3
	v_ashrrev_i32_e32 v4, 6, v4
	v_add_u32_e32 v7, v5, v3
	v_lshlrev_b32_e32 v8, 3, v4
	v_ashrrev_i32_e32 v3, 6, v7
	v_and_b32_e32 v8, -16, v8
	v_add_u32_e32 v8, v3, v8
	v_and_b32_e32 v9, 3, v3
	s_ashr_i32 s11, s5, 6
	v_and_or_b32 v9, v8, s1, v9
	v_readlane_b32 s1, v255, 24
	v_readlane_b32 s8, v255, 22
	s_ashr_i32 s24, s5, 8
	s_lshl_b32 s7, s11, 10
	s_lshl_b32 s13, s1, 5
	v_readlane_b32 s9, v255, 23
	s_mul_i32 s10, s1, 33
	s_and_b64 s[8:9], s[8:9], exec
	s_cselect_b32 s8, s10, s13
	v_readlane_b32 s1, v255, 21
	s_add_i32 s8, s8, s1
	s_ashr_i32 s9, s8, 31
	s_lshr_b32 s9, s9, 27
	s_add_i32 s9, s8, s9
	s_ashr_i32 s10, s9, 5
	s_and_b32 s9, s9, 0xffe0
	s_sub_i32 s8, s8, s9
	s_bfe_i32 s9, s8, 0x80000
	s_bfe_u32 s9, s9, 0x3000c
	s_add_i32 s9, s8, s9
	s_lshl_b32 s13, s10, 3
	s_bfe_i32 s10, s9, 0x80000
	s_and_b32 s9, s9, 0xf8
	s_sub_i32 s8, s8, s9
	s_sext_i32_i16 s10, s10
	s_sext_i32_i8 s8, s8
	v_lshrrev_b32_e32 v10, 2, v8
	v_lshlrev_b32_e32 v11, 1, v8
	v_and_b32_e32 v7, 0xc0, v7
	s_lshr_b32 s10, s10, 3
	s_add_i32 s22, s13, s8
	v_and_b32_e32 v10, 4, v10
	v_and_b32_e32 v11, 24, v11
	v_sub_u32_e32 v5, v5, v7
	s_ashr_i32 s23, s22, 31
	s_bfe_i64 s[8:9], s[10:11], 0x100000
	v_or3_b32 v9, v9, v10, v11
	v_lshlrev_b32_e32 v10, 5, v4
	v_ashrrev_i16_sdwa v5, v252, sext(v5) dst_sel:DWORD dst_unused:UNUSED_PAD src0_sel:DWORD src1_sel:BYTE_0
	s_lshl_b64 s[20:21], s[22:23], 18
	s_lshl_b64 s[8:9], s[8:9], 18
	v_and_b32_e32 v10, 32, v10
	v_bfe_i32 v5, v5, 0, 16
	s_add_u32 s44, s4, s8
	v_readlane_b32 s1, v255, 32
	v_add_lshl_u32 v7, v10, v5, 1
	s_addc_u32 s45, s1, s9
	s_add_i32 s8, s7, 0
	v_lshl_add_u32 v200, v9, 10, v7
	s_add_i32 m0, s8, 0x10000
	v_readlane_b32 s12, v254, 63
	global_load_lds_dwordx4 v200, s[44:45]
	s_add_i32 m0, s8, 0x12000
	s_add_u32 s28, s44, 0x20000
	global_load_lds_dwordx4 v128, s[44:45]
	s_addc_u32 s29, s45, 0
	s_add_i32 m0, s8, 0x14000
	v_lshl_add_u32 v132, v8, 10, v7
	global_load_lds_dwordx4 v200, s[28:29]
	s_add_i32 m0, s8, 0x16000
	s_add_u32 s84, s12, s20
	s_addc_u32 s85, s3, s21
	s_add_i32 s9, s8, 0x2000
	global_load_lds_dwordx4 v128, s[28:29]
	v_readlane_b32 s13, v255, 0
	s_mov_b32 m0, s8
	s_add_u32 s20, s84, 0x20000
	v_readlane_b32 s15, v255, 2
	global_load_lds_dwordx4 v132, s[84:85]
	s_mov_b32 m0, s9
	s_addc_u32 s21, s85, 0
	s_add_i32 s13, s8, 0x4000
	global_load_lds_dwordx4 v130, s[84:85]
	s_mov_b32 m0, s13
	s_add_i32 s15, s8, 0x6000
	global_load_lds_dwordx4 v132, s[20:21]
	s_mov_b32 m0, s15
	s_cmp_eq_u32 s24, 1
	global_load_lds_dwordx4 v130, s[20:21]
	s_cselect_b64 s[20:21], -1, 0
	s_cmp_lg_u32 s24, 1
	v_readlane_b32 s14, v255, 1
	s_cbranch_scc1 .LBB0_609
	s_barrier

; __device__ __forceinline__ unsigned xb_ld(unsigned* p)              { return __hip_atomic_load(p, __ATOMIC_RELAXED, __HIP_MEMORY_SCOPE_AGENT); }
; __device__ __forceinline__ unsigned xb_add(unsigned* p, unsigned v) { return __hip_atomic_fetch_add(p, v, __ATOMIC_RELAXED, __HIP_MEMORY_SCOPE_AGENT); }
; #define XB_SPIN(cond, bar) do { unsigned _sp = 0; while (cond) { __builtin_amdgcn_s_sleep(1); \
;     if ((++_sp & 255u) == 0u) { if (xb_ld(&(bar)[XB_TMO])) break; if (_sp > XB_SPIN_CAP) { atomicAdd(&(bar)[XB_TMO], 1u); break; } } } } while (0)
; __device__ __forceinline__ void xcd_barrier(const XcdBarrier& b) {
;     asm volatile("s_waitcnt vmcnt(0)" ::: "memory");
;     __syncthreads();
;     if (threadIdx.x == 0) {
;         unsigned* bar = b.bar;
;         __builtin_amdgcn_s_waitcnt(0);
;         unsigned nloc = b.st[0], nx = b.st[1];
;         if (nloc == 0u) { xcd_barrier_complete(bar, b.x, nloc, nx); b.st[0] = nloc; b.st[1] = nx; }
;         const unsigned old = xb_add(&bar[XB_XSUB(b.x)], 1u);
;         const unsigned gen = old / nloc;
;         if (old + 1u == (gen + 1u) * nloc) {
;             __builtin_amdgcn_fence(__ATOMIC_RELEASE, "agent");
;             asm volatile("s_waitcnt vmcnt(0)" ::: "memory");
;             const unsigned og = xb_add(&bar[XB_TOP], 1u);
;             const unsigned tg = og / nx;
;             __builtin_amdgcn_fence(__ATOMIC_ACQUIRE, "agent");
;             if (og + 1u == (tg + 1u) * nx) xb_add(&bar[XB_TOPGEN], 1u);
;             else XB_SPIN(xb_ld(&bar[XB_TOPGEN]) == tg, bar);
;             xb_add(&bar[XB_XGEN(b.x)], 1u);
;             asm volatile("s_waitcnt vmcnt(0)" ::: "memory");
;         } else {
;             __builtin_amdgcn_fence(__ATOMIC_ACQUIRE, "agent");
;             XB_SPIN(xb_ld(&bar[XB_XGEN(b.x)]) == gen, bar);
;             asm volatile("s_waitcnt vmcnt(0)" ::: "memory");
;         }
;     }
;     __syncthreads();
; }
.LBB0_626:
	s_waitcnt vmcnt(0)
	s_waitcnt vmcnt(0) lgkmcnt(0)
	s_barrier
	s_mov_b64 s[4:5], exec
	v_readlane_b32 s8, v253, 41
	v_readlane_b32 s9, v253, 42
	s_and_b64 s[8:9], s[4:5], s[8:9]
	s_mov_b64 exec, s[8:9]
	s_cbranch_execz .LBB0_678
	s_waitcnt vmcnt(0) lgkmcnt(0)
	v_readlane_b32 s22, v255, 54
	v_readlane_b32 s24, v254, 51
	v_readlane_b32 s8, v254, 25
	v_readlane_b32 s9, v254, 26
	v_readlane_b32 s20, v254, 27
	v_readlane_b32 s21, v254, 28
	s_add_u32 s22, s22, 1
	v_mov_b32_e32 v0, s24
	ds_read_b32 v2, v0
	s_add_u32 s8, s8, 0x2c00
	s_addc_u32 s9, s9, 0
	s_add_u32 s20, s20, 0x2c00
	s_addc_u32 s21, s21, 0
	v_writelane_b32 v255, s22, 54
	v_mov_b32_e32 v1, 1
	v_mov_b32_e32 v3, 0
	s_nop 1
	global_atomic_add v4, v3, v1, s[8:9] sc0
	s_waitcnt vmcnt(0) lgkmcnt(0)
	v_readfirstlane_b32 s24, v4
	v_readfirstlane_b32 s23, v2
	s_add_u32 s24, s24, 1
	s_mul_i32 s25, s23, s22
	s_cmp_lg_u32 s24, s25
	s_cbranch_scc1 .Lgd_notlast_2
	buffer_wbl2 sc1
	s_waitcnt vmcnt(0)
	v_readlane_b32 s8, v254, 29
	v_readlane_b32 s9, v254, 30
	v_mov_b32_e32 v5, s23
	s_add_u32 s8, s8, 0x1c00
	s_addc_u32 s9, s9, 0
	s_nop 4
	global_atomic_add v3, v5, s[8:9]
	global_atomic_add v3, v5, s[8:9] offset:256
	global_atomic_add v3, v5, s[8:9] offset:512
	global_atomic_add v3, v5, s[8:9] offset:768
	global_atomic_add v3, v5, s[8:9] offset:1024
	global_atomic_add v3, v5, s[8:9] offset:1280
	global_atomic_add v3, v5, s[8:9] offset:1536
	global_atomic_add v3, v5, s[8:9] offset:1792
	global_atomic_add v3, v5, s[8:9] offset:2048
	global_atomic_add v3, v5, s[8:9] offset:2304
	global_atomic_add v3, v5, s[8:9] offset:2560
	global_atomic_add v3, v5, s[8:9] offset:2816
	global_atomic_add v3, v5, s[8:9] offset:3072
	global_atomic_add v3, v5, s[8:9] offset:3328
	global_atomic_add v3, v5, s[8:9] offset:3584
	global_atomic_add v3, v5, s[8:9] offset:3840

; __device__ __forceinline__ unsigned xb_ld(unsigned* p)              { return __hip_atomic_load(p, __ATOMIC_RELAXED, __HIP_MEMORY_SCOPE_AGENT); }
; __device__ __forceinline__ unsigned xb_add(unsigned* p, unsigned v) { return __hip_atomic_fetch_add(p, v, __ATOMIC_RELAXED, __HIP_MEMORY_SCOPE_AGENT); }
; #define XB_SPIN(cond, bar) do { unsigned _sp = 0; while (cond) { __builtin_amdgcn_s_sleep(1); \
;     if ((++_sp & 255u) == 0u) { if (xb_ld(&(bar)[XB_TMO])) break; if (_sp > XB_SPIN_CAP) { atomicAdd(&(bar)[XB_TMO], 1u); break; } } } } while (0)
; __device__ __forceinline__ void xcd_barrier(const XcdBarrier& b) {
;     asm volatile("s_waitcnt vmcnt(0)" ::: "memory");
;     __syncthreads();
;     if (threadIdx.x == 0) {
;         unsigned* bar = b.bar;
;         __builtin_amdgcn_s_waitcnt(0);
;         unsigned nloc = b.st[0], nx = b.st[1];
;         if (nloc == 0u) { xcd_barrier_complete(bar, b.x, nloc, nx); b.st[0] = nloc; b.st[1] = nx; }
;         const unsigned old = xb_add(&bar[XB_XSUB(b.x)], 1u);
;         const unsigned gen = old / nloc;
;         if (old + 1u == (gen + 1u) * nloc) {
;             __builtin_amdgcn_fence(__ATOMIC_RELEASE, "agent");
;             asm volatile("s_waitcnt vmcnt(0)" ::: "memory");
;             const unsigned og = xb_add(&bar[XB_TOP], 1u);
;             const unsigned tg = og / nx;
;             __builtin_amdgcn_fence(__ATOMIC_ACQUIRE, "agent");
;             if (og + 1u == (tg + 1u) * nx) xb_add(&bar[XB_TOPGEN], 1u);
;             else XB_SPIN(xb_ld(&bar[XB_TOPGEN]) == tg, bar);
;             xb_add(&bar[XB_XGEN(b.x)], 1u);
;             asm volatile("s_waitcnt vmcnt(0)" ::: "memory");
;         } else {
;             __builtin_amdgcn_fence(__ATOMIC_ACQUIRE, "agent");
;             XB_SPIN(xb_ld(&bar[XB_XGEN(b.x)]) == gen, bar);
;             asm volatile("s_waitcnt vmcnt(0)" ::: "memory");
;         }
;     }
;     __syncthreads();
; }
; __global__ void __launch_bounds__(512, 2) mk_fwd(Args a) {
;     ...
;         {
;             pg8::Gemm g{MIX, WOUT, DM, DM, DM, 0, 0}; pg8::StaticOrder S; S.init(NTOK, DM, G, bx);
;             EpiRes E{layer == 0 ? a.x : nullptr, nullptr, XN, PART};
;             pg8::gemm_phase<EpiRes, pg8::StaticOrder>(lds, g, S, E);
.Lgd_done_2:
	s_waitcnt vmcnt(0)
.LBB0_678:
	s_or_b64 exec, exec, s[4:5]
	v_readlane_b32 s4, v255, 45
	v_mov_b32_e32 v8, v236
	v_readlane_b32 s5, v255, 46
	s_waitcnt lgkmcnt(0)
	s_barrier
	s_and_b64 vcc, exec, s[4:5]
	v_readfirstlane_b32 s10, v8
	s_cbranch_vccz .LBB0_684
	v_readlane_b32 s8, v255, 25
	v_readlane_b32 s9, v255, 26
	s_mov_b64 s[4:5], -1
	s_and_b64 vcc, exec, s[8:9]
	s_cbranch_vccz .LBB0_681
	v_readlane_b32 s1, v255, 24
	s_lshl_b32 s7, s1, 5
	s_mov_b64 s[4:5], 0

; __device__ __forceinline__ unsigned xb_ld(unsigned* p)              { return __hip_atomic_load(p, __ATOMIC_RELAXED, __HIP_MEMORY_SCOPE_AGENT); }
; __device__ __forceinline__ unsigned xb_add(unsigned* p, unsigned v) { return __hip_atomic_fetch_add(p, v, __ATOMIC_RELAXED, __HIP_MEMORY_SCOPE_AGENT); }
; #define XB_SPIN(cond, bar) do { unsigned _sp = 0; while (cond) { __builtin_amdgcn_s_sleep(1); \
;     if ((++_sp & 255u) == 0u) { if (xb_ld(&(bar)[XB_TMO])) break; if (_sp > XB_SPIN_CAP) { atomicAdd(&(bar)[XB_TMO], 1u); break; } } } } while (0)
; __device__ __forceinline__ void xcd_barrier(const XcdBarrier& b) {
;     asm volatile("s_waitcnt vmcnt(0)" ::: "memory");
;     __syncthreads();
;     if (threadIdx.x == 0) {
;         unsigned* bar = b.bar;
;         __builtin_amdgcn_s_waitcnt(0);
;         unsigned nloc = b.st[0], nx = b.st[1];
;         if (nloc == 0u) { xcd_barrier_complete(bar, b.x, nloc, nx); b.st[0] = nloc; b.st[1] = nx; }
;         const unsigned old = xb_add(&bar[XB_XSUB(b.x)], 1u);
;         const unsigned gen = old / nloc;
;         if (old + 1u == (gen + 1u) * nloc) {
;             __builtin_amdgcn_fence(__ATOMIC_RELEASE, "agent");
;             asm volatile("s_waitcnt vmcnt(0)" ::: "memory");
;             const unsigned og = xb_add(&bar[XB_TOP], 1u);
;             const unsigned tg = og / nx;
;             __builtin_amdgcn_fence(__ATOMIC_ACQUIRE, "agent");
;             if (og + 1u == (tg + 1u) * nx) xb_add(&bar[XB_TOPGEN], 1u);
;             else XB_SPIN(xb_ld(&bar[XB_TOPGEN]) == tg, bar);
;             xb_add(&bar[XB_XGEN(b.x)], 1u);
;             asm volatile("s_waitcnt vmcnt(0)" ::: "memory");
;         } else {
;             __builtin_amdgcn_fence(__ATOMIC_ACQUIRE, "agent");
;             XB_SPIN(xb_ld(&bar[XB_XGEN(b.x)]) == gen, bar);
;             asm volatile("s_waitcnt vmcnt(0)" ::: "memory");
;         }
;     }
;     __syncthreads();
; }
.LBB0_789:
	s_waitcnt vmcnt(0)
	v_readlane_b32 s0, v253, 41
	v_readlane_b32 s1, v253, 42
	s_waitcnt lgkmcnt(0)
	s_barrier
	s_and_saveexec_b64 s[4:5], s[0:1]
	s_cbranch_execz .LBB0_841
	s_waitcnt vmcnt(0) lgkmcnt(0)
	v_readlane_b32 s22, v255, 54
	v_readlane_b32 s24, v254, 51
	v_readlane_b32 s8, v254, 25
	v_readlane_b32 s9, v254, 26
	v_readlane_b32 s20, v254, 27
	v_readlane_b32 s21, v254, 28
	s_add_u32 s22, s22, 1
	v_mov_b32_e32 v0, s24
	ds_read_b32 v2, v0
	s_add_u32 s8, s8, 0x2c00
	s_addc_u32 s9, s9, 0
	s_add_u32 s20, s20, 0x2c00
	s_addc_u32 s21, s21, 0
	v_writelane_b32 v255, s22, 54
	v_mov_b32_e32 v1, 1
	v_mov_b32_e32 v3, 0
	s_nop 1
	global_atomic_add v4, v3, v1, s[8:9] sc0
	s_waitcnt vmcnt(0) lgkmcnt(0)
	v_readfirstlane_b32 s24, v4
	v_readfirstlane_b32 s23, v2
	s_add_u32 s24, s24, 1
	s_mul_i32 s25, s23, s22
	s_cmp_lg_u32 s24, s25
	s_cbranch_scc1 .Lgd_notlast_3
	buffer_wbl2 sc1
	s_waitcnt vmcnt(0)
	v_readlane_b32 s8, v254, 29
	v_readlane_b32 s9, v254, 30
	v_mov_b32_e32 v5, s23
	s_add_u32 s8, s8, 0x1c00
	s_addc_u32 s9, s9, 0
	s_nop 4
	global_atomic_add v3, v5, s[8:9]
	global_atomic_add v3, v5, s[8:9] offset:256
	global_atomic_add v3, v5, s[8:9] offset:512
	global_atomic_add v3, v5, s[8:9] offset:768
	global_atomic_add v3, v5, s[8:9] offset:1024
	global_atomic_add v3, v5, s[8:9] offset:1280
	global_atomic_add v3, v5, s[8:9] offset:1536
	global_atomic_add v3, v5, s[8:9] offset:1792
	global_atomic_add v3, v5, s[8:9] offset:2048
	global_atomic_add v3, v5, s[8:9] offset:2304
	global_atomic_add v3, v5, s[8:9] offset:2560
	global_atomic_add v3, v5, s[8:9] offset:2816
	global_atomic_add v3, v5, s[8:9] offset:3072
	global_atomic_add v3, v5, s[8:9] offset:3328
	global_atomic_add v3, v5, s[8:9] offset:3584
	global_atomic_add v3, v5, s[8:9] offset:3840

; #define LAS __attribute__((address_space(3)))
;     __device__ bool next(int i, Unit& u) const {
;         const long L = (long)i * G + c; if (L >= nwg) return false;
;         int wgid = (int)L; { const int q = nwg / NXCD, r = nwg % NXCD, xcd = wgid % NXCD, off = wgid / NXCD; wgid = (xcd < r ? xcd * (q + 1) : r * (q + 1) + (xcd - r) * q) + off; }
;         const int nig = WGM * nN, gid = wgid / nig, fm = gid * WGM, gsz = (nM - fm) < WGM ? (nM - fm) : WGM;
;         u.pm = fm + ((wgid % nig) % gsz); u.pn = (wgid % nig) / gsz; u.g = 0; return true;
;     }
; __global__ void __launch_bounds__(512, 2) mk_fwd(Args a) {
;     ...
;         for (int rp = 0; rp < REP_P7; ++rp) {
;             pg8::Gemm g{XN, W1, DM, DM, DM, 0, 0}; pg8::StaticOrder S; S.init(NTOK, FF, G, bx);
;             LAS float* rsl = (LAS float*)(lds + 131072);
;             pg8::RsPre pre{PART, rsl, 0, 0, 0};
;             { Unit u0; if (S.next(0, u0)) { pre.pm0 = u0.pm; pre.ntab = 1; } }
.Lgd_done_3:
	s_waitcnt vmcnt(0)
.LBB0_841:
	s_or_b64 exec, exec, s[4:5]
	s_cmpk_lt_i32 s49, 0x400
	v_readlane_b32 s0, v255, 24
	s_cselect_b64 s[4:5], -1, 0
	s_lshl_b32 s8, s0, 7
	s_cmpk_gt_i32 s49, 0x3ff
	s_mul_i32 s9, s0, 0x81
	s_mov_b32 s13, 0
	s_waitcnt lgkmcnt(0)
	s_barrier
	s_cbranch_scc1 .LBB0_843
	v_readlane_b32 s0, v255, 22
	v_readlane_b32 s1, v255, 23
	s_and_b64 s[10:11], s[0:1], exec
	s_cselect_b32 s7, s9, s8
	v_readlane_b32 s0, v255, 21
	s_add_i32 s7, s7, s0
	s_ashr_i32 s10, s7, 31
	s_lshr_b32 s10, s10, 25
	s_add_i32 s10, s7, s10
	s_ashr_i32 s11, s10, 7
	s_lshl_b32 s11, s11, 3
	s_sub_i32 s12, 64, s11
	s_min_i32 s12, s12, 8
	s_abs_i32 s12, s12
	v_cvt_f32_u32_e32 v0, s12
	s_sub_i32 s13, 0, s12
	s_and_b32 s10, s10, 0xffffff80
	s_sub_i32 s7, s7, s10
	v_rcp_iflag_f32_e32 v0, v0
	s_ashr_i32 s10, s7, 31
	s_abs_i32 s7, s7
	v_mul_f32_e32 v0, 0x4f7ffffe, v0
	v_cvt_u32_f32_e32 v0, v0
	s_nop 0
	v_readfirstlane_b32 s15, v0
	s_mul_i32 s13, s13, s15
	s_mul_hi_u32 s13, s15, s13
	s_add_i32 s15, s15, s13
	s_mul_hi_u32 s13, s7, s15
	s_mul_i32 s13, s13, s12
	s_sub_i32 s7, s7, s13
	s_sub_i32 s13, s7, s12
	s_cmp_ge_u32 s7, s12
	s_cselect_b32 s7, s13, s7
	s_sub_i32 s13, s7, s12
	s_cmp_ge_u32 s7, s12
	s_cselect_b32 s7, s13, s7
	s_xor_b32 s7, s7, s10
	s_sub_i32 s7, s7, s10
	s_add_i32 s11, s11, s7
	s_lshl_b32 s13, s11, 8

; __device__ __forceinline__ unsigned xb_ld(unsigned* p)              { return __hip_atomic_load(p, __ATOMIC_RELAXED, __HIP_MEMORY_SCOPE_AGENT); }
; __device__ __forceinline__ unsigned xb_add(unsigned* p, unsigned v) { return __hip_atomic_fetch_add(p, v, __ATOMIC_RELAXED, __HIP_MEMORY_SCOPE_AGENT); }
; #define XB_SPIN(cond, bar) do { unsigned _sp = 0; while (cond) { __builtin_amdgcn_s_sleep(1); \
;     if ((++_sp & 255u) == 0u) { if (xb_ld(&(bar)[XB_TMO])) break; if (_sp > XB_SPIN_CAP) { atomicAdd(&(bar)[XB_TMO], 1u); break; } } } } while (0)
; __device__ __forceinline__ void xcd_barrier(const XcdBarrier& b) {
;     asm volatile("s_waitcnt vmcnt(0)" ::: "memory");
;     __syncthreads();
;     if (threadIdx.x == 0) {
;         unsigned* bar = b.bar;
;         __builtin_amdgcn_s_waitcnt(0);
;         unsigned nloc = b.st[0], nx = b.st[1];
;         if (nloc == 0u) { xcd_barrier_complete(bar, b.x, nloc, nx); b.st[0] = nloc; b.st[1] = nx; }
;         const unsigned old = xb_add(&bar[XB_XSUB(b.x)], 1u);
;         const unsigned gen = old / nloc;
;         if (old + 1u == (gen + 1u) * nloc) {
;             __builtin_amdgcn_fence(__ATOMIC_RELEASE, "agent");
;             asm volatile("s_waitcnt vmcnt(0)" ::: "memory");
;             const unsigned og = xb_add(&bar[XB_TOP], 1u);
;             const unsigned tg = og / nx;
;             __builtin_amdgcn_fence(__ATOMIC_ACQUIRE, "agent");
;             if (og + 1u == (tg + 1u) * nx) xb_add(&bar[XB_TOPGEN], 1u);
;             else XB_SPIN(xb_ld(&bar[XB_TOPGEN]) == tg, bar);
;             xb_add(&bar[XB_XGEN(b.x)], 1u);
;             asm volatile("s_waitcnt vmcnt(0)" ::: "memory");
;         } else {
;             __builtin_amdgcn_fence(__ATOMIC_ACQUIRE, "agent");
;             XB_SPIN(xb_ld(&bar[XB_XGEN(b.x)]) == gen, bar);
;             asm volatile("s_waitcnt vmcnt(0)" ::: "memory");
;         }
;     }
;     __syncthreads();
; }
.LBB0_865:
	s_waitcnt vmcnt(0)
	v_readlane_b32 s0, v253, 41
	v_readlane_b32 s1, v253, 42
	s_waitcnt vmcnt(0)
	s_barrier
	s_and_saveexec_b64 s[4:5], s[0:1]
	s_cbranch_execz .LBB0_917
	s_waitcnt vmcnt(0) lgkmcnt(0)
	v_readlane_b32 s22, v255, 54
	v_readlane_b32 s24, v254, 51
	v_readlane_b32 s8, v254, 25
	v_readlane_b32 s9, v254, 26
	v_readlane_b32 s20, v254, 27
	v_readlane_b32 s21, v254, 28
	s_add_u32 s22, s22, 1
	v_mov_b32_e32 v0, s24
	ds_read_b32 v2, v0
	s_add_u32 s8, s8, 0x2c00
	s_addc_u32 s9, s9, 0
	s_add_u32 s20, s20, 0x2c00
	s_addc_u32 s21, s21, 0
	v_writelane_b32 v255, s22, 54
	v_mov_b32_e32 v1, 1
	v_mov_b32_e32 v3, 0
	s_nop 1
	global_atomic_add v4, v3, v1, s[8:9] sc0
	s_waitcnt vmcnt(0) lgkmcnt(0)
	v_readfirstlane_b32 s24, v4
	v_readfirstlane_b32 s23, v2
	s_add_u32 s24, s24, 1
	s_mul_i32 s25, s23, s22
	s_cmp_lg_u32 s24, s25
	s_cbranch_scc1 .Lgd_notlast_4
	buffer_wbl2 sc1
	s_waitcnt vmcnt(0)
	v_readlane_b32 s8, v254, 29
	v_readlane_b32 s9, v254, 30
	v_mov_b32_e32 v5, s23
	s_add_u32 s8, s8, 0x1c00
	s_addc_u32 s9, s9, 0
	s_nop 4
	global_atomic_add v3, v5, s[8:9]
	global_atomic_add v3, v5, s[8:9] offset:256
	global_atomic_add v3, v5, s[8:9] offset:512
	global_atomic_add v3, v5, s[8:9] offset:768
	global_atomic_add v3, v5, s[8:9] offset:1024
	global_atomic_add v3, v5, s[8:9] offset:1280
	global_atomic_add v3, v5, s[8:9] offset:1536
	global_atomic_add v3, v5, s[8:9] offset:1792
	global_atomic_add v3, v5, s[8:9] offset:2048
	global_atomic_add v3, v5, s[8:9] offset:2304
	global_atomic_add v3, v5, s[8:9] offset:2560
	global_atomic_add v3, v5, s[8:9] offset:2816
	global_atomic_add v3, v5, s[8:9] offset:3072
	global_atomic_add v3, v5, s[8:9] offset:3328
	global_atomic_add v3, v5, s[8:9] offset:3584
	global_atomic_add v3, v5, s[8:9] offset:3840

; __device__ __forceinline__ unsigned xb_ld(unsigned* p)              { return __hip_atomic_load(p, __ATOMIC_RELAXED, __HIP_MEMORY_SCOPE_AGENT); }
; __device__ __forceinline__ unsigned xb_add(unsigned* p, unsigned v) { return __hip_atomic_fetch_add(p, v, __ATOMIC_RELAXED, __HIP_MEMORY_SCOPE_AGENT); }
; #define XB_SPIN(cond, bar) do { unsigned _sp = 0; while (cond) { __builtin_amdgcn_s_sleep(1); \
;     if ((++_sp & 255u) == 0u) { if (xb_ld(&(bar)[XB_TMO])) break; if (_sp > XB_SPIN_CAP) { atomicAdd(&(bar)[XB_TMO], 1u); break; } } } } while (0)
; __device__ __forceinline__ void xcd_barrier(const XcdBarrier& b) {
;     asm volatile("s_waitcnt vmcnt(0)" ::: "memory");
;     __syncthreads();
;     if (threadIdx.x == 0) {
;         unsigned* bar = b.bar;
;         __builtin_amdgcn_s_waitcnt(0);
;         unsigned nloc = b.st[0], nx = b.st[1];
;         if (nloc == 0u) { xcd_barrier_complete(bar, b.x, nloc, nx); b.st[0] = nloc; b.st[1] = nx; }
;         const unsigned old = xb_add(&bar[XB_XSUB(b.x)], 1u);
;         const unsigned gen = old / nloc;
;         if (old + 1u == (gen + 1u) * nloc) {
;             __builtin_amdgcn_fence(__ATOMIC_RELEASE, "agent");
;             asm volatile("s_waitcnt vmcnt(0)" ::: "memory");
;             const unsigned og = xb_add(&bar[XB_TOP], 1u);
;             const unsigned tg = og / nx;
;             __builtin_amdgcn_fence(__ATOMIC_ACQUIRE, "agent");
;             if (og + 1u == (tg + 1u) * nx) xb_add(&bar[XB_TOPGEN], 1u);
;             else XB_SPIN(xb_ld(&bar[XB_TOPGEN]) == tg, bar);
;             xb_add(&bar[XB_XGEN(b.x)], 1u);
;             asm volatile("s_waitcnt vmcnt(0)" ::: "memory");
;         } else {
;             __builtin_amdgcn_fence(__ATOMIC_ACQUIRE, "agent");
;             XB_SPIN(xb_ld(&bar[XB_XGEN(b.x)]) == gen, bar);
;             asm volatile("s_waitcnt vmcnt(0)" ::: "memory");
;         }
;     }
;     __syncthreads();
; }
; __global__ void __launch_bounds__(512, 2) mk_fwd(Args a) {
;     ...
;         {
;             pg8::Gemm g{HID, W2, FF, FF, FF, 0, 0}; pg8::StaticOrder S; S.init(NTOK, DM, G, bx);
;             EpiRes E{nullptr, layer == DEPTH - 1 ? a.out : nullptr, XN, PART};
;             pg8::gemm_phase<EpiRes, pg8::StaticOrder>(lds, g, S, E);
.Lgd_done_4:
	s_waitcnt vmcnt(0)
.LBB0_917:
	s_or_b64 exec, exec, s[4:5]
	v_readlane_b32 s0, v255, 45
	v_mov_b32_e32 v8, v236
	v_readlane_b32 s1, v255, 46
	s_waitcnt lgkmcnt(0)
	s_barrier
	s_and_b64 vcc, exec, s[0:1]
	v_readfirstlane_b32 s12, v8
	s_cbranch_vccz .LBB0_923
	v_readlane_b32 s0, v255, 25
	v_readlane_b32 s1, v255, 26
	s_mov_b64 s[4:5], -1
	s_and_b64 vcc, exec, s[0:1]
	s_cbranch_vccz .LBB0_920
	v_readlane_b32 s0, v255, 24
	s_lshl_b32 s7, s0, 5
	s_mov_b64 s[4:5], 0

; __device__ __forceinline__ unsigned xb_ld(unsigned* p)              { return __hip_atomic_load(p, __ATOMIC_RELAXED, __HIP_MEMORY_SCOPE_AGENT); }
; __device__ __forceinline__ unsigned xb_add(unsigned* p, unsigned v) { return __hip_atomic_fetch_add(p, v, __ATOMIC_RELAXED, __HIP_MEMORY_SCOPE_AGENT); }
; #define XB_SPIN(cond, bar) do { unsigned _sp = 0; while (cond) { __builtin_amdgcn_s_sleep(1); \
;     if ((++_sp & 255u) == 0u) { if (xb_ld(&(bar)[XB_TMO])) break; if (_sp > XB_SPIN_CAP) { atomicAdd(&(bar)[XB_TMO], 1u); break; } } } } while (0)
; __device__ __forceinline__ void xcd_barrier(const XcdBarrier& b) {
;     asm volatile("s_waitcnt vmcnt(0)" ::: "memory");
;     __syncthreads();
;     if (threadIdx.x == 0) {
;         unsigned* bar = b.bar;
;         __builtin_amdgcn_s_waitcnt(0);
;         unsigned nloc = b.st[0], nx = b.st[1];
;         if (nloc == 0u) { xcd_barrier_complete(bar, b.x, nloc, nx); b.st[0] = nloc; b.st[1] = nx; }
;         const unsigned old = xb_add(&bar[XB_XSUB(b.x)], 1u);
;         const unsigned gen = old / nloc;
;         if (old + 1u == (gen + 1u) * nloc) {
;             __builtin_amdgcn_fence(__ATOMIC_RELEASE, "agent");
;             asm volatile("s_waitcnt vmcnt(0)" ::: "memory");
;             const unsigned og = xb_add(&bar[XB_TOP], 1u);
;             const unsigned tg = og / nx;
;             __builtin_amdgcn_fence(__ATOMIC_ACQUIRE, "agent");
;             if (og + 1u == (tg + 1u) * nx) xb_add(&bar[XB_TOPGEN], 1u);
;             else XB_SPIN(xb_ld(&bar[XB_TOPGEN]) == tg, bar);
;             xb_add(&bar[XB_XGEN(b.x)], 1u);
;             asm volatile("s_waitcnt vmcnt(0)" ::: "memory");
;         } else {
;             __builtin_amdgcn_fence(__ATOMIC_ACQUIRE, "agent");
;             XB_SPIN(xb_ld(&bar[XB_XGEN(b.x)]) == gen, bar);
;             asm volatile("s_waitcnt vmcnt(0)" ::: "memory");
;         }
;     }
;     __syncthreads();
; }
.LBB0_1025:
	s_waitcnt vmcnt(0) lgkmcnt(0)
	v_readlane_b32 s22, v255, 54
	v_readlane_b32 s24, v254, 51
	v_readlane_b32 s8, v254, 25
	v_readlane_b32 s9, v254, 26
	v_readlane_b32 s20, v254, 27
	v_readlane_b32 s21, v254, 28
	s_add_u32 s22, s22, 1
	v_mov_b32_e32 v0, s24
	ds_read_b32 v2, v0
	s_add_u32 s8, s8, 0x2c00
	s_addc_u32 s9, s9, 0
	s_add_u32 s20, s20, 0x2c00
	s_addc_u32 s21, s21, 0
	v_writelane_b32 v255, s22, 54
	v_mov_b32_e32 v1, 1
	v_mov_b32_e32 v3, 0
	s_nop 1
	global_atomic_add v4, v3, v1, s[8:9] sc0
	s_waitcnt vmcnt(0) lgkmcnt(0)
	v_readfirstlane_b32 s24, v4
	v_readfirstlane_b32 s23, v2
	s_add_u32 s24, s24, 1
	s_mul_i32 s25, s23, s22
	s_cmp_lg_u32 s24, s25
	s_cbranch_scc1 .Lgd_notlast_5
	buffer_wbl2 sc1
	s_waitcnt vmcnt(0)
	v_readlane_b32 s8, v254, 29
	v_readlane_b32 s9, v254, 30
	v_mov_b32_e32 v5, s23
	s_add_u32 s8, s8, 0x1c00
	s_addc_u32 s9, s9, 0
	s_nop 4
	global_atomic_add v3, v5, s[8:9]
	global_atomic_add v3, v5, s[8:9] offset:256
	global_atomic_add v3, v5, s[8:9] offset:512
	global_atomic_add v3, v5, s[8:9] offset:768
	global_atomic_add v3, v5, s[8:9] offset:1024
	global_atomic_add v3, v5, s[8:9] offset:1280
	global_atomic_add v3, v5, s[8:9] offset:1536
	global_atomic_add v3, v5, s[8:9] offset:1792
	global_atomic_add v3, v5, s[8:9] offset:2048
	global_atomic_add v3, v5, s[8:9] offset:2304
	global_atomic_add v3, v5, s[8:9] offset:2560
	global_atomic_add v3, v5, s[8:9] offset:2816
	global_atomic_add v3, v5, s[8:9] offset:3072
	global_atomic_add v3, v5, s[8:9] offset:3328
	global_atomic_add v3, v5, s[8:9] offset:3584
	global_atomic_add v3, v5, s[8:9] offset:3840

; #define GSYNC() do { for (int rs_ = 0; rs_ < REP_SYNC; ++rs_) xcd_barrier(xbar); } while (0)
; __device__ __forceinline__ unsigned xb_ld(unsigned* p)              { return __hip_atomic_load(p, __ATOMIC_RELAXED, __HIP_MEMORY_SCOPE_AGENT); }
; __device__ __forceinline__ unsigned xb_add(unsigned* p, unsigned v) { return __hip_atomic_fetch_add(p, v, __ATOMIC_RELAXED, __HIP_MEMORY_SCOPE_AGENT); }
; #define XB_SPIN(cond, bar) do { unsigned _sp = 0; while (cond) { __builtin_amdgcn_s_sleep(1); \
;     if ((++_sp & 255u) == 0u) { if (xb_ld(&(bar)[XB_TMO])) break; if (_sp > XB_SPIN_CAP) { atomicAdd(&(bar)[XB_TMO], 1u); break; } } } } while (0)
; __device__ __forceinline__ void xcd_barrier(const XcdBarrier& b) {
;     asm volatile("s_waitcnt vmcnt(0)" ::: "memory");
;     __syncthreads();
;     if (threadIdx.x == 0) {
;         unsigned* bar = b.bar;
;         __builtin_amdgcn_s_waitcnt(0);
;         unsigned nloc = b.st[0], nx = b.st[1];
;         if (nloc == 0u) { xcd_barrier_complete(bar, b.x, nloc, nx); b.st[0] = nloc; b.st[1] = nx; }
;         const unsigned old = xb_add(&bar[XB_XSUB(b.x)], 1u);
;         const unsigned gen = old / nloc;
;         if (old + 1u == (gen + 1u) * nloc) {
;             __builtin_amdgcn_fence(__ATOMIC_RELEASE, "agent");
;             asm volatile("s_waitcnt vmcnt(0)" ::: "memory");
;             const unsigned og = xb_add(&bar[XB_TOP], 1u);
;             const unsigned tg = og / nx;
;             __builtin_amdgcn_fence(__ATOMIC_ACQUIRE, "agent");
;             if (og + 1u == (tg + 1u) * nx) xb_add(&bar[XB_TOPGEN], 1u);
;             else XB_SPIN(xb_ld(&bar[XB_TOPGEN]) == tg, bar);
;             xb_add(&bar[XB_XGEN(b.x)], 1u);
;             asm volatile("s_waitcnt vmcnt(0)" ::: "memory");
;         } else {
;             __builtin_amdgcn_fence(__ATOMIC_ACQUIRE, "agent");
;             XB_SPIN(xb_ld(&bar[XB_XGEN(b.x)]) == gen, bar);
;             asm volatile("s_waitcnt vmcnt(0)" ::: "memory");
;         }
;     }
;     __syncthreads();
; }
; __global__ void __launch_bounds__(512, 2) mk_fwd(Args a) {
;     ...
;         if (layer + 1 < DEPTH) GSYNC();
;     }
.Lgd_done_5:
	s_waitcnt vmcnt(0)
	s_mov_b64 s[8:9], 0
	s_getpc_b64 s[98:99]
